# v060 + G1 epilogue stores (P, QN, KN, kv-cache outputs) write-through (sc1): nothing of them left dirty in L2 for the grid barrier's write-back
# baseline (speedup 1.0000x reference)
; __device__ __forceinline__ u32x4 pack8(f32x4 v0, f32x4 v1) { u32x4 w; w.x = cvt_pk_bf16(v0[0], v0[1]); w.y = cvt_pk_bf16(v0[2], v0[3]); w.z = cvt_pk_bf16(v1[0], v1[1]); w.w = cvt_pk_bf16(v1[2], v1[3]); return w; }
; __device__ __forceinline__ void unpack8(u32x4 w, f32x4& v0, f32x4& v1) { v0 = (f32x4){bflo(w.x), bfhi(w.x), bflo(w.y), bfhi(w.y)}; v1 = (f32x4){bflo(w.z), bfhi(w.z), bflo(w.w), bfhi(w.w)}; }
;     __device__ __forceinline__ void operator()(const f32x4 (&acc)[2][2][4][2], const Unit& u, int wr, int wc, int fr_in, int fq_in) const {
;     ...
;         const int col0 = u.pn * BM + wc * 32 + 8 * fq;
;         const bool isg = u.pn >= 10, isv = u.pn == 9;
;         bf16_t* const pbase = P + (size_t)row0 * NPJ + col0;
;         f32x4 bv[2][2];
; #pragma unroll
;         for (int bj = 0; bj < 2; ++bj)
; #pragma unroll
;             for (int n = 0; n < 2; ++n) bv[bj][n] = isg ? *(const f32x4*)(bgate + (col0 - 2560) + bj * HALF + 4 * n) : (f32x4){0.f, 0.f, 0.f, 0.f};
; #pragma unroll
;         for (int ai = 0; ai < 2; ++ai)
; #pragma unroll
;             for (int m = 0; m < 4; ++m) { const int row = row0 + ai * HALF + m * 16; bf16_t* rowp = pbase + (size_t)(ai * HALF + m * 16) * NPJ;
; #pragma unroll
;                 for (int bj = 0; bj < 2; ++bj) { f32x4 v0 = acc[ai][bj][m][0] + bv[bj][0], v1 = acc[ai][bj][m][1] + bv[bj][1];
;                     if (isg) { v0 = sigmoid4(v0); v1 = sigmoid4(v1); }
;                     const u32x4 w = pack8(v0, v1); store16_wt(rowp + bj * HALF, w);
;                     if (isv) { const bool smp = row >= 8192; const int t = smp ? ((row - 8192) & 63) : (row & 2047); const int bb = smp ? ((row - 8192) >> 6) : (row >> 11);
;                         if (smp || t >= 1920) { float* d = out + (smp ? o_sv + ((size_t)(l * 16 + bb) * 128 + 64 + t) * 256 : o_pv + ((size_t)(l * 4 + bb) * 128 + (t - 1920)) * 256) + (col0 - 2304) + bj * HALF;
;                             f32x4 r0, r1; unpack8(w, r0, r1); *(f32x4*)(d) = r0; *(f32x4*)(d + 4) = r1; } } } }
.LBB0_286:
	v_mov_b64_e32 v[154:155], s[20:21]
	s_movk_i32 s0, 0x3400
	v_mad_i64_i32 v[154:155], s[0:1], v192, s0, v[154:155]
	s_movk_i32 s0, 0x1fff
	s_nop 0
	v_cmp_lt_i32_e64 s[40:41], s0, v192
	s_movk_i32 s0, 0x2000
	v_and_b32_e32 v156, 0x7ff, v192
	s_cmp_lg_u32 s95, 9
	v_cmp_gt_i32_e64 s[42:43], s0, v192
	v_add_u32_e32 v157, 0xffffe000, v192
	v_subrev_co_u32_e32 v156, vcc, 0x780, v156
	v_lshlrev_b32_e32 v162, 8, v224
	s_cselect_b64 s[56:57], -1, 0
	v_lshrrev_b32_e32 v164, 6, v157
	s_and_b64 s[0:1], s[42:43], vcc
	v_ashrrev_i32_e32 v157, 31, v156
	v_and_b32_e32 v162, 0x3f00, v162
	v_lshl_add_u64 v[154:155], v[152:153], 1, v[154:155]
	v_ashrrev_i32_e32 v163, 11, v192
	v_lshlrev_b64 v[156:157], 8, v[156:157]
	v_or_b32_e32 v162, 0x4000, v162
	v_cvt_pk_bf16_f32 v148, v148, v149
	v_cvt_pk_bf16_f32 v149, v160, v161
	v_cvt_pk_bf16_f32 v150, v150, v151
	v_cvt_pk_bf16_f32 v151, v158, v159
	s_nor_b64 s[42:43], s[56:57], s[0:1]
	global_store_dwordx4 v[154:155], v[148:151], off sc1
	s_and_saveexec_b64 s[58:59], s[42:43]
	s_cbranch_execz .LBB0_292
	s_and_saveexec_b64 s[0:1], s[40:41]
	s_xor_b64 s[60:61], exec, s[0:1]
	v_add_u32_e32 v158, s31, v164
	v_mov_b32_e32 v159, v98
	v_lshlrev_b64 v[158:159], 15, v[158:159]
	v_or_b32_e32 v158, v158, v162
	s_mov_b64 s[0:1], 0x1520000
	v_lshl_add_u64 v[158:159], v[158:159], 0, s[0:1]
	s_andn2_saveexec_b64 s[60:61], s[60:61]
	v_add_u32_e32 v158, s75, v163
	v_ashrrev_i32_e32 v159, 31, v158
	v_lshlrev_b64 v[158:159], 15, v[158:159]
	v_lshl_add_u64 v[158:159], v[156:157], 0, v[158:159]
	s_mov_b64 s[0:1], 0x1280000
	v_lshl_add_u64 v[158:159], v[158:159], 0, s[0:1]
	s_or_b64 exec, exec, s[60:61]
	v_readlane_b32 s60, v251, 14
	v_readlane_b32 s64, v251, 18
	v_readlane_b32 s65, v251, 19
	v_readlane_b32 s61, v251, 15
	v_readlane_b32 s62, v251, 16
	v_lshl_add_u64 v[158:159], v[158:159], 2, s[64:65]
	v_lshl_add_u64 v[166:167], v[152:153], 2, v[158:159]
	v_add_co_u32_e32 v166, vcc, 0xffffe000, v166
	v_readlane_b32 s63, v251, 17
	v_readlane_b32 s66, v251, 20
	v_readlane_b32 s67, v251, 21
	v_lshlrev_b32_e32 v158, 16, v148
	v_and_b32_e32 v159, 0xffff0000, v148
	v_lshlrev_b32_e32 v160, 16, v149
	v_and_b32_e32 v161, 0xffff0000, v149
	v_addc_co_u32_e32 v167, vcc, -1, v167, vcc
	v_lshlrev_b32_e32 v148, 16, v150
	v_and_b32_e32 v149, 0xffff0000, v150
	v_lshlrev_b32_e32 v150, 16, v151
	v_and_b32_e32 v151, 0xffff0000, v151
	global_store_dwordx4 v[166:167], v[158:161], off offset:-1024 sc1
	global_store_dwordx4 v[166:167], v[148:151], off offset:-1008 sc1

; __device__ __forceinline__ u32x4 pack8(f32x4 v0, f32x4 v1) { u32x4 w; w.x = cvt_pk_bf16(v0[0], v0[1]); w.y = cvt_pk_bf16(v0[2], v0[3]); w.z = cvt_pk_bf16(v1[0], v1[1]); w.w = cvt_pk_bf16(v1[2], v1[3]); return w; }
; __device__ __forceinline__ void unpack8(u32x4 w, f32x4& v0, f32x4& v1) { v0 = (f32x4){bflo(w.x), bfhi(w.x), bflo(w.y), bfhi(w.y)}; v1 = (f32x4){bflo(w.z), bfhi(w.z), bflo(w.w), bfhi(w.w)}; }
;     __device__ __forceinline__ void operator()(const f32x4 (&acc)[2][2][4][2], const Unit& u, int wr, int wc, int fr_in, int fq_in) const {
;     ...
;             for (int m = 0; m < 4; ++m) { const int row = row0 + ai * HALF + m * 16; bf16_t* rowp = pbase + (size_t)(ai * HALF + m * 16) * NPJ;
; #pragma unroll
;                 for (int bj = 0; bj < 2; ++bj) { f32x4 v0 = acc[ai][bj][m][0] + bv[bj][0], v1 = acc[ai][bj][m][1] + bv[bj][1];
;                     if (isg) { v0 = sigmoid4(v0); v1 = sigmoid4(v1); }
;                     const u32x4 w = pack8(v0, v1); store16_wt(rowp + bj * HALF, w);
;                     if (isv) { const bool smp = row >= 8192; const int t = smp ? ((row - 8192) & 63) : (row & 2047); const int bb = smp ? ((row - 8192) >> 6) : (row >> 11);
;                         if (smp || t >= 1920) { float* d = out + (smp ? o_sv + ((size_t)(l * 16 + bb) * 128 + 64 + t) * 256 : o_pv + ((size_t)(l * 4 + bb) * 128 + (t - 1920)) * 256) + (col0 - 2304) + bj * HALF;
;                             f32x4 r0, r1; unpack8(w, r0, r1); *(f32x4*)(d) = r0; *(f32x4*)(d + 4) = r1; } } } }
.LBB0_296:
	v_cvt_pk_bf16_f32 v148, v148, v149
	v_cvt_pk_bf16_f32 v149, v160, v161
	v_cvt_pk_bf16_f32 v150, v150, v151
	v_cvt_pk_bf16_f32 v151, v158, v159
	global_store_dwordx4 v[154:155], v[148:151], off offset:256 sc1
	s_and_saveexec_b64 s[58:59], s[42:43]
	s_cbranch_execz .LBB0_302
	s_and_saveexec_b64 s[0:1], s[40:41]
	s_xor_b64 s[40:41], exec, s[0:1]
	v_add_u32_e32 v156, s31, v164
	v_mov_b32_e32 v157, v98
	v_lshlrev_b64 v[156:157], 15, v[156:157]
	v_or_b32_e32 v156, v156, v162
	s_mov_b64 s[0:1], 0x1520000
	v_lshl_add_u64 v[158:159], v[156:157], 0, s[0:1]
	s_andn2_saveexec_b64 s[40:41], s[40:41]
	v_add_u32_e32 v158, s75, v163
	v_ashrrev_i32_e32 v159, 31, v158
	v_lshlrev_b64 v[158:159], 15, v[158:159]
	v_lshl_add_u64 v[156:157], v[156:157], 0, v[158:159]
	s_mov_b64 s[0:1], 0x1280000
	v_lshl_add_u64 v[158:159], v[156:157], 0, s[0:1]
	s_or_b64 exec, exec, s[40:41]
	v_lshl_add_u64 v[156:157], v[158:159], 2, s[64:65]
	v_lshl_add_u64 v[160:161], v[152:153], 2, v[156:157]
	v_add_co_u32_e32 v160, vcc, 0xffffe000, v160
	v_lshlrev_b32_e32 v156, 16, v148
	v_and_b32_e32 v157, 0xffff0000, v148
	v_lshlrev_b32_e32 v158, 16, v149
	v_and_b32_e32 v159, 0xffff0000, v149
	v_addc_co_u32_e32 v161, vcc, -1, v161, vcc
	v_lshlrev_b32_e32 v148, 16, v150
	v_and_b32_e32 v149, 0xffff0000, v150
	v_lshlrev_b32_e32 v150, 16, v151
	v_and_b32_e32 v151, 0xffff0000, v151
	global_store_dwordx4 v[160:161], v[156:159], off offset:-512 sc1
	global_store_dwordx4 v[160:161], v[148:151], off offset:-496 sc1

; __device__ __forceinline__ u32x4 pack8(f32x4 v0, f32x4 v1) { u32x4 w; w.x = cvt_pk_bf16(v0[0], v0[1]); w.y = cvt_pk_bf16(v0[2], v0[3]); w.z = cvt_pk_bf16(v1[0], v1[1]); w.w = cvt_pk_bf16(v1[2], v1[3]); return w; }
; __device__ __forceinline__ void unpack8(u32x4 w, f32x4& v0, f32x4& v1) { v0 = (f32x4){bflo(w.x), bfhi(w.x), bflo(w.y), bfhi(w.y)}; v1 = (f32x4){bflo(w.z), bfhi(w.z), bflo(w.w), bfhi(w.w)}; }
;     __device__ __forceinline__ void operator()(const f32x4 (&acc)[2][2][4][2], const Unit& u, int wr, int wc, int fr_in, int fq_in) const {
;     ...
;             for (int m = 0; m < 4; ++m) { const int row = row0 + ai * HALF + m * 16; bf16_t* rowp = pbase + (size_t)(ai * HALF + m * 16) * NPJ;
; #pragma unroll
;                 for (int bj = 0; bj < 2; ++bj) { f32x4 v0 = acc[ai][bj][m][0] + bv[bj][0], v1 = acc[ai][bj][m][1] + bv[bj][1];
;                     if (isg) { v0 = sigmoid4(v0); v1 = sigmoid4(v1); }
;                     const u32x4 w = pack8(v0, v1); store16_wt(rowp + bj * HALF, w);
;                     if (isv) { const bool smp = row >= 8192; const int t = smp ? ((row - 8192) & 63) : (row & 2047); const int bb = smp ? ((row - 8192) >> 6) : (row >> 11);
;                         if (smp || t >= 1920) { float* d = out + (smp ? o_sv + ((size_t)(l * 16 + bb) * 128 + 64 + t) * 256 : o_pv + ((size_t)(l * 4 + bb) * 128 + (t - 1920)) * 256) + (col0 - 2304) + bj * HALF;
;                             f32x4 r0, r1; unpack8(w, r0, r1); *(f32x4*)(d) = r0; *(f32x4*)(d + 4) = r1; } } } }
.LBB0_306:
	v_add_u32_e32 v165, 16, v192
	s_movk_i32 s0, 0x1fef
	v_cmp_lt_i32_e64 s[40:41], s0, v192
	s_movk_i32 s0, 0x1ff0
	v_and_b32_e32 v156, 0x7ff, v165
	v_cmp_gt_i32_e64 s[42:43], s0, v192
	v_add_u32_e32 v157, 0xffffe010, v192
	v_ashrrev_i32_e32 v163, 11, v165
	v_subrev_co_u32_e32 v156, vcc, 0x780, v156
	v_lshlrev_b32_e32 v165, 8, v165
	v_lshrrev_b32_e32 v164, 6, v157
	s_and_b64 s[0:1], s[42:43], vcc
	v_ashrrev_i32_e32 v157, 31, v156
	v_and_b32_e32 v165, 0x3f00, v165
	v_cvt_pk_bf16_f32 v150, v150, v151
	v_cvt_pk_bf16_f32 v151, v158, v159
	v_add_co_u32_e32 v158, vcc, 0x34000, v154
	v_lshlrev_b64 v[156:157], 8, v[156:157]
	v_or_b32_e32 v165, 0x4000, v165
	v_cvt_pk_bf16_f32 v148, v148, v149
	v_cvt_pk_bf16_f32 v149, v160, v161
	v_addc_co_u32_e32 v159, vcc, 0, v155, vcc
	s_nor_b64 s[42:43], s[56:57], s[0:1]
	global_store_dwordx4 v[158:159], v[148:151], off sc1
	s_and_saveexec_b64 s[58:59], s[42:43]
	s_cbranch_execz .LBB0_312
	s_and_saveexec_b64 s[0:1], s[40:41]
	s_xor_b64 s[60:61], exec, s[0:1]
	v_add_u32_e32 v158, s31, v164
	v_mov_b32_e32 v159, v98
	v_lshlrev_b64 v[158:159], 15, v[158:159]
	v_or_b32_e32 v158, v158, v165
	s_mov_b64 s[0:1], 0x1520000
	v_lshl_add_u64 v[158:159], v[158:159], 0, s[0:1]
	s_andn2_saveexec_b64 s[60:61], s[60:61]
	v_add_u32_e32 v158, s75, v163
	v_ashrrev_i32_e32 v159, 31, v158
	v_lshlrev_b64 v[158:159], 15, v[158:159]
	v_lshl_add_u64 v[158:159], v[156:157], 0, v[158:159]
	s_mov_b64 s[0:1], 0x1280000
	v_lshl_add_u64 v[158:159], v[158:159], 0, s[0:1]
	s_or_b64 exec, exec, s[60:61]
	v_readlane_b32 s60, v251, 14
	v_readlane_b32 s64, v251, 18
	v_readlane_b32 s65, v251, 19
	v_readlane_b32 s61, v251, 15
	v_readlane_b32 s62, v251, 16
	v_lshl_add_u64 v[158:159], v[158:159], 2, s[64:65]
	v_lshl_add_u64 v[166:167], v[152:153], 2, v[158:159]
	v_add_co_u32_e32 v166, vcc, 0xffffe000, v166
	v_readlane_b32 s63, v251, 17
	v_readlane_b32 s66, v251, 20
	v_readlane_b32 s67, v251, 21
	v_lshlrev_b32_e32 v158, 16, v148
	v_and_b32_e32 v159, 0xffff0000, v148
	v_lshlrev_b32_e32 v160, 16, v149
	v_and_b32_e32 v161, 0xffff0000, v149
	v_addc_co_u32_e32 v167, vcc, -1, v167, vcc
	v_lshlrev_b32_e32 v148, 16, v150
	v_and_b32_e32 v149, 0xffff0000, v150
	v_lshlrev_b32_e32 v150, 16, v151
	v_and_b32_e32 v151, 0xffff0000, v151
	global_store_dwordx4 v[166:167], v[158:161], off offset:-1024 sc1
	global_store_dwordx4 v[166:167], v[148:151], off offset:-1008 sc1

; __device__ __forceinline__ u32x4 pack8(f32x4 v0, f32x4 v1) { u32x4 w; w.x = cvt_pk_bf16(v0[0], v0[1]); w.y = cvt_pk_bf16(v0[2], v0[3]); w.z = cvt_pk_bf16(v1[0], v1[1]); w.w = cvt_pk_bf16(v1[2], v1[3]); return w; }
; __device__ __forceinline__ void unpack8(u32x4 w, f32x4& v0, f32x4& v1) { v0 = (f32x4){bflo(w.x), bfhi(w.x), bflo(w.y), bfhi(w.y)}; v1 = (f32x4){bflo(w.z), bfhi(w.z), bflo(w.w), bfhi(w.w)}; }
;     __device__ __forceinline__ void operator()(const f32x4 (&acc)[2][2][4][2], const Unit& u, int wr, int wc, int fr_in, int fq_in) const {
;     ...
;             for (int m = 0; m < 4; ++m) { const int row = row0 + ai * HALF + m * 16; bf16_t* rowp = pbase + (size_t)(ai * HALF + m * 16) * NPJ;
; #pragma unroll
;                 for (int bj = 0; bj < 2; ++bj) { f32x4 v0 = acc[ai][bj][m][0] + bv[bj][0], v1 = acc[ai][bj][m][1] + bv[bj][1];
;                     if (isg) { v0 = sigmoid4(v0); v1 = sigmoid4(v1); }
;                     const u32x4 w = pack8(v0, v1); store16_wt(rowp + bj * HALF, w);
;                     if (isv) { const bool smp = row >= 8192; const int t = smp ? ((row - 8192) & 63) : (row & 2047); const int bb = smp ? ((row - 8192) >> 6) : (row >> 11);
;                         if (smp || t >= 1920) { float* d = out + (smp ? o_sv + ((size_t)(l * 16 + bb) * 128 + 64 + t) * 256 : o_pv + ((size_t)(l * 4 + bb) * 128 + (t - 1920)) * 256) + (col0 - 2304) + bj * HALF;
;                             f32x4 r0, r1; unpack8(w, r0, r1); *(f32x4*)(d) = r0; *(f32x4*)(d + 4) = r1; } } } }
.LBB0_316:
	v_cvt_pk_bf16_f32 v150, v150, v151
	v_cvt_pk_bf16_f32 v151, v158, v159
	v_add_co_u32_e32 v158, vcc, 0x34000, v154
	v_cvt_pk_bf16_f32 v148, v148, v149
	v_cvt_pk_bf16_f32 v149, v160, v161
	v_addc_co_u32_e32 v159, vcc, 0, v155, vcc
	global_store_dwordx4 v[158:159], v[148:151], off offset:256 sc1
	s_and_saveexec_b64 s[58:59], s[42:43]
	s_cbranch_execz .LBB0_322
	s_and_saveexec_b64 s[0:1], s[40:41]
	s_xor_b64 s[40:41], exec, s[0:1]
	v_add_u32_e32 v156, s31, v164
	v_mov_b32_e32 v157, v98
	v_lshlrev_b64 v[156:157], 15, v[156:157]
	v_or_b32_e32 v156, v156, v165
	s_mov_b64 s[0:1], 0x1520000
	v_lshl_add_u64 v[158:159], v[156:157], 0, s[0:1]
	s_andn2_saveexec_b64 s[40:41], s[40:41]
	v_add_u32_e32 v158, s75, v163
	v_ashrrev_i32_e32 v159, 31, v158
	v_lshlrev_b64 v[158:159], 15, v[158:159]
	v_lshl_add_u64 v[156:157], v[156:157], 0, v[158:159]
	s_mov_b64 s[0:1], 0x1280000
	v_lshl_add_u64 v[158:159], v[156:157], 0, s[0:1]
	s_or_b64 exec, exec, s[40:41]
	v_lshl_add_u64 v[156:157], v[158:159], 2, s[64:65]
	v_lshl_add_u64 v[160:161], v[152:153], 2, v[156:157]
	v_add_co_u32_e32 v160, vcc, 0xffffe000, v160
	v_lshlrev_b32_e32 v156, 16, v148
	v_and_b32_e32 v157, 0xffff0000, v148
	v_lshlrev_b32_e32 v158, 16, v149
	v_and_b32_e32 v159, 0xffff0000, v149
	v_addc_co_u32_e32 v161, vcc, -1, v161, vcc
	v_lshlrev_b32_e32 v148, 16, v150
	v_and_b32_e32 v149, 0xffff0000, v150
	v_lshlrev_b32_e32 v150, 16, v151
	v_and_b32_e32 v151, 0xffff0000, v151
	global_store_dwordx4 v[160:161], v[156:159], off offset:-512 sc1
	global_store_dwordx4 v[160:161], v[148:151], off offset:-496 sc1

; __device__ __forceinline__ u32x4 pack8(f32x4 v0, f32x4 v1) { u32x4 w; w.x = cvt_pk_bf16(v0[0], v0[1]); w.y = cvt_pk_bf16(v0[2], v0[3]); w.z = cvt_pk_bf16(v1[0], v1[1]); w.w = cvt_pk_bf16(v1[2], v1[3]); return w; }
; __device__ __forceinline__ void unpack8(u32x4 w, f32x4& v0, f32x4& v1) { v0 = (f32x4){bflo(w.x), bfhi(w.x), bflo(w.y), bfhi(w.y)}; v1 = (f32x4){bflo(w.z), bfhi(w.z), bflo(w.w), bfhi(w.w)}; }
;     __device__ __forceinline__ void operator()(const f32x4 (&acc)[2][2][4][2], const Unit& u, int wr, int wc, int fr_in, int fq_in) const {
;     ...
;             for (int m = 0; m < 4; ++m) { const int row = row0 + ai * HALF + m * 16; bf16_t* rowp = pbase + (size_t)(ai * HALF + m * 16) * NPJ;
; #pragma unroll
;                 for (int bj = 0; bj < 2; ++bj) { f32x4 v0 = acc[ai][bj][m][0] + bv[bj][0], v1 = acc[ai][bj][m][1] + bv[bj][1];
;                     if (isg) { v0 = sigmoid4(v0); v1 = sigmoid4(v1); }
;                     const u32x4 w = pack8(v0, v1); store16_wt(rowp + bj * HALF, w);
;                     if (isv) { const bool smp = row >= 8192; const int t = smp ? ((row - 8192) & 63) : (row & 2047); const int bb = smp ? ((row - 8192) >> 6) : (row >> 11);
;                         if (smp || t >= 1920) { float* d = out + (smp ? o_sv + ((size_t)(l * 16 + bb) * 128 + 64 + t) * 256 : o_pv + ((size_t)(l * 4 + bb) * 128 + (t - 1920)) * 256) + (col0 - 2304) + bj * HALF;
;                             f32x4 r0, r1; unpack8(w, r0, r1); *(f32x4*)(d) = r0; *(f32x4*)(d + 4) = r1; } } } }
.LBB0_326:
	v_add_u32_e32 v165, 32, v192
	s_movk_i32 s0, 0x1fdf
	v_cmp_lt_i32_e64 s[40:41], s0, v192
	s_movk_i32 s0, 0x1fe0
	v_and_b32_e32 v156, 0x7ff, v165
	v_cmp_gt_i32_e64 s[42:43], s0, v192
	v_add_u32_e32 v157, 0xffffe020, v192
	v_ashrrev_i32_e32 v163, 11, v165
	v_subrev_co_u32_e32 v156, vcc, 0x780, v156
	v_lshlrev_b32_e32 v165, 8, v165
	v_lshrrev_b32_e32 v164, 6, v157
	s_and_b64 s[0:1], s[42:43], vcc
	v_ashrrev_i32_e32 v157, 31, v156
	v_and_b32_e32 v165, 0x3f00, v165
	v_cvt_pk_bf16_f32 v150, v150, v151
	v_cvt_pk_bf16_f32 v151, v158, v159
	v_add_co_u32_e32 v158, vcc, 0x68000, v154
	v_lshlrev_b64 v[156:157], 8, v[156:157]
	v_or_b32_e32 v165, 0x4000, v165
	v_cvt_pk_bf16_f32 v148, v148, v149
	v_cvt_pk_bf16_f32 v149, v160, v161
	v_addc_co_u32_e32 v159, vcc, 0, v155, vcc
	s_nor_b64 s[42:43], s[56:57], s[0:1]
	global_store_dwordx4 v[158:159], v[148:151], off sc1
	s_and_saveexec_b64 s[58:59], s[42:43]
	s_cbranch_execz .LBB0_332
	s_and_saveexec_b64 s[0:1], s[40:41]
	s_xor_b64 s[60:61], exec, s[0:1]
	v_add_u32_e32 v158, s31, v164
	v_mov_b32_e32 v159, v98
	v_lshlrev_b64 v[158:159], 15, v[158:159]
	v_or_b32_e32 v158, v158, v165
	s_mov_b64 s[0:1], 0x1520000
	v_lshl_add_u64 v[158:159], v[158:159], 0, s[0:1]
	s_andn2_saveexec_b64 s[60:61], s[60:61]
	v_add_u32_e32 v158, s75, v163
	v_ashrrev_i32_e32 v159, 31, v158
	v_lshlrev_b64 v[158:159], 15, v[158:159]
	v_lshl_add_u64 v[158:159], v[156:157], 0, v[158:159]
	s_mov_b64 s[0:1], 0x1280000
	v_lshl_add_u64 v[158:159], v[158:159], 0, s[0:1]
	s_or_b64 exec, exec, s[60:61]
	v_readlane_b32 s60, v251, 14
	v_readlane_b32 s64, v251, 18
	v_readlane_b32 s65, v251, 19
	v_readlane_b32 s61, v251, 15
	v_readlane_b32 s62, v251, 16
	v_lshl_add_u64 v[158:159], v[158:159], 2, s[64:65]
	v_lshl_add_u64 v[166:167], v[152:153], 2, v[158:159]
	v_add_co_u32_e32 v166, vcc, 0xffffe000, v166
	v_readlane_b32 s63, v251, 17
	v_readlane_b32 s66, v251, 20
	v_readlane_b32 s67, v251, 21
	v_lshlrev_b32_e32 v158, 16, v148
	v_and_b32_e32 v159, 0xffff0000, v148
	v_lshlrev_b32_e32 v160, 16, v149
	v_and_b32_e32 v161, 0xffff0000, v149
	v_addc_co_u32_e32 v167, vcc, -1, v167, vcc
	v_lshlrev_b32_e32 v148, 16, v150
	v_and_b32_e32 v149, 0xffff0000, v150
	v_lshlrev_b32_e32 v150, 16, v151
	v_and_b32_e32 v151, 0xffff0000, v151
	global_store_dwordx4 v[166:167], v[158:161], off offset:-1024 sc1
	global_store_dwordx4 v[166:167], v[148:151], off offset:-1008 sc1

; __device__ __forceinline__ u32x4 pack8(f32x4 v0, f32x4 v1) { u32x4 w; w.x = cvt_pk_bf16(v0[0], v0[1]); w.y = cvt_pk_bf16(v0[2], v0[3]); w.z = cvt_pk_bf16(v1[0], v1[1]); w.w = cvt_pk_bf16(v1[2], v1[3]); return w; }
; __device__ __forceinline__ void unpack8(u32x4 w, f32x4& v0, f32x4& v1) { v0 = (f32x4){bflo(w.x), bfhi(w.x), bflo(w.y), bfhi(w.y)}; v1 = (f32x4){bflo(w.z), bfhi(w.z), bflo(w.w), bfhi(w.w)}; }
;     __device__ __forceinline__ void operator()(const f32x4 (&acc)[2][2][4][2], const Unit& u, int wr, int wc, int fr_in, int fq_in) const {
;     ...
;             for (int m = 0; m < 4; ++m) { const int row = row0 + ai * HALF + m * 16; bf16_t* rowp = pbase + (size_t)(ai * HALF + m * 16) * NPJ;
; #pragma unroll
;                 for (int bj = 0; bj < 2; ++bj) { f32x4 v0 = acc[ai][bj][m][0] + bv[bj][0], v1 = acc[ai][bj][m][1] + bv[bj][1];
;                     if (isg) { v0 = sigmoid4(v0); v1 = sigmoid4(v1); }
;                     const u32x4 w = pack8(v0, v1); store16_wt(rowp + bj * HALF, w);
;                     if (isv) { const bool smp = row >= 8192; const int t = smp ? ((row - 8192) & 63) : (row & 2047); const int bb = smp ? ((row - 8192) >> 6) : (row >> 11);
;                         if (smp || t >= 1920) { float* d = out + (smp ? o_sv + ((size_t)(l * 16 + bb) * 128 + 64 + t) * 256 : o_pv + ((size_t)(l * 4 + bb) * 128 + (t - 1920)) * 256) + (col0 - 2304) + bj * HALF;
;                             f32x4 r0, r1; unpack8(w, r0, r1); *(f32x4*)(d) = r0; *(f32x4*)(d + 4) = r1; } } } }
.LBB0_336:
	v_cvt_pk_bf16_f32 v150, v150, v151
	v_cvt_pk_bf16_f32 v151, v158, v159
	v_add_co_u32_e32 v158, vcc, 0x68000, v154
	v_cvt_pk_bf16_f32 v148, v148, v149
	v_cvt_pk_bf16_f32 v149, v160, v161
	v_addc_co_u32_e32 v159, vcc, 0, v155, vcc
	global_store_dwordx4 v[158:159], v[148:151], off offset:256 sc1
	s_and_saveexec_b64 s[58:59], s[42:43]
	s_cbranch_execz .LBB0_342
	s_and_saveexec_b64 s[0:1], s[40:41]
	s_xor_b64 s[40:41], exec, s[0:1]
	v_add_u32_e32 v156, s31, v164
	v_mov_b32_e32 v157, v98
	v_lshlrev_b64 v[156:157], 15, v[156:157]
	v_or_b32_e32 v156, v156, v165
	s_mov_b64 s[0:1], 0x1520000
	v_lshl_add_u64 v[158:159], v[156:157], 0, s[0:1]
	s_andn2_saveexec_b64 s[40:41], s[40:41]
	v_add_u32_e32 v158, s75, v163
	v_ashrrev_i32_e32 v159, 31, v158
	v_lshlrev_b64 v[158:159], 15, v[158:159]
	v_lshl_add_u64 v[156:157], v[156:157], 0, v[158:159]
	s_mov_b64 s[0:1], 0x1280000
	v_lshl_add_u64 v[158:159], v[156:157], 0, s[0:1]
	s_or_b64 exec, exec, s[40:41]
	v_lshl_add_u64 v[156:157], v[158:159], 2, s[64:65]
	v_lshl_add_u64 v[160:161], v[152:153], 2, v[156:157]
	v_add_co_u32_e32 v160, vcc, 0xffffe000, v160
	v_lshlrev_b32_e32 v156, 16, v148
	v_and_b32_e32 v157, 0xffff0000, v148
	v_lshlrev_b32_e32 v158, 16, v149
	v_and_b32_e32 v159, 0xffff0000, v149
	v_addc_co_u32_e32 v161, vcc, -1, v161, vcc
	v_lshlrev_b32_e32 v148, 16, v150
	v_and_b32_e32 v149, 0xffff0000, v150
	v_lshlrev_b32_e32 v150, 16, v151
	v_and_b32_e32 v151, 0xffff0000, v151
	global_store_dwordx4 v[160:161], v[156:159], off offset:-512 sc1
	global_store_dwordx4 v[160:161], v[148:151], off offset:-496 sc1

; __device__ __forceinline__ u32x4 pack8(f32x4 v0, f32x4 v1) { u32x4 w; w.x = cvt_pk_bf16(v0[0], v0[1]); w.y = cvt_pk_bf16(v0[2], v0[3]); w.z = cvt_pk_bf16(v1[0], v1[1]); w.w = cvt_pk_bf16(v1[2], v1[3]); return w; }
; __device__ __forceinline__ void unpack8(u32x4 w, f32x4& v0, f32x4& v1) { v0 = (f32x4){bflo(w.x), bfhi(w.x), bflo(w.y), bfhi(w.y)}; v1 = (f32x4){bflo(w.z), bfhi(w.z), bflo(w.w), bfhi(w.w)}; }
;     __device__ __forceinline__ void operator()(const f32x4 (&acc)[2][2][4][2], const Unit& u, int wr, int wc, int fr_in, int fq_in) const {
;     ...
;             for (int m = 0; m < 4; ++m) { const int row = row0 + ai * HALF + m * 16; bf16_t* rowp = pbase + (size_t)(ai * HALF + m * 16) * NPJ;
; #pragma unroll
;                 for (int bj = 0; bj < 2; ++bj) { f32x4 v0 = acc[ai][bj][m][0] + bv[bj][0], v1 = acc[ai][bj][m][1] + bv[bj][1];
;                     if (isg) { v0 = sigmoid4(v0); v1 = sigmoid4(v1); }
;                     const u32x4 w = pack8(v0, v1); store16_wt(rowp + bj * HALF, w);
;                     if (isv) { const bool smp = row >= 8192; const int t = smp ? ((row - 8192) & 63) : (row & 2047); const int bb = smp ? ((row - 8192) >> 6) : (row >> 11);
;                         if (smp || t >= 1920) { float* d = out + (smp ? o_sv + ((size_t)(l * 16 + bb) * 128 + 64 + t) * 256 : o_pv + ((size_t)(l * 4 + bb) * 128 + (t - 1920)) * 256) + (col0 - 2304) + bj * HALF;
;                             f32x4 r0, r1; unpack8(w, r0, r1); *(f32x4*)(d) = r0; *(f32x4*)(d + 4) = r1; } } } }
.LBB0_346:
	v_add_u32_e32 v165, 48, v192
	s_movk_i32 s0, 0x1fcf
	v_cmp_lt_i32_e64 s[40:41], s0, v192
	s_movk_i32 s0, 0x1fd0
	v_and_b32_e32 v156, 0x7ff, v165
	v_cmp_gt_i32_e64 s[42:43], s0, v192
	v_add_u32_e32 v157, 0xffffe030, v192
	v_ashrrev_i32_e32 v163, 11, v165
	v_subrev_co_u32_e32 v156, vcc, 0x780, v156
	v_lshlrev_b32_e32 v165, 8, v165
	v_lshrrev_b32_e32 v164, 6, v157
	s_and_b64 s[0:1], s[42:43], vcc
	v_ashrrev_i32_e32 v157, 31, v156
	v_and_b32_e32 v165, 0x3f00, v165
	v_cvt_pk_bf16_f32 v150, v150, v151
	v_cvt_pk_bf16_f32 v151, v158, v159
	v_add_co_u32_e32 v158, vcc, 0x9c000, v154
	v_lshlrev_b64 v[156:157], 8, v[156:157]
	v_or_b32_e32 v165, 0x4000, v165
	v_cvt_pk_bf16_f32 v148, v148, v149
	v_cvt_pk_bf16_f32 v149, v160, v161
	v_addc_co_u32_e32 v159, vcc, 0, v155, vcc
	s_nor_b64 s[42:43], s[56:57], s[0:1]
	global_store_dwordx4 v[158:159], v[148:151], off sc1
	s_and_saveexec_b64 s[58:59], s[42:43]
	s_cbranch_execz .LBB0_352
	s_and_saveexec_b64 s[0:1], s[40:41]
	s_xor_b64 s[60:61], exec, s[0:1]
	v_add_u32_e32 v158, s31, v164
	v_mov_b32_e32 v159, v98
	v_lshlrev_b64 v[158:159], 15, v[158:159]
	v_or_b32_e32 v158, v158, v165
	s_mov_b64 s[0:1], 0x1520000
	v_lshl_add_u64 v[158:159], v[158:159], 0, s[0:1]
	s_andn2_saveexec_b64 s[60:61], s[60:61]
	v_add_u32_e32 v158, s75, v163
	v_ashrrev_i32_e32 v159, 31, v158
	v_lshlrev_b64 v[158:159], 15, v[158:159]
	v_lshl_add_u64 v[158:159], v[156:157], 0, v[158:159]
	s_mov_b64 s[0:1], 0x1280000
	v_lshl_add_u64 v[158:159], v[158:159], 0, s[0:1]
	s_or_b64 exec, exec, s[60:61]
	v_readlane_b32 s60, v251, 14
	v_readlane_b32 s64, v251, 18
	v_readlane_b32 s65, v251, 19
	v_readlane_b32 s61, v251, 15
	v_readlane_b32 s62, v251, 16
	v_lshl_add_u64 v[158:159], v[158:159], 2, s[64:65]
	v_lshl_add_u64 v[166:167], v[152:153], 2, v[158:159]
	v_add_co_u32_e32 v166, vcc, 0xffffe000, v166
	v_readlane_b32 s63, v251, 17
	v_readlane_b32 s66, v251, 20
	v_readlane_b32 s67, v251, 21
	v_lshlrev_b32_e32 v158, 16, v148
	v_and_b32_e32 v159, 0xffff0000, v148
	v_lshlrev_b32_e32 v160, 16, v149
	v_and_b32_e32 v161, 0xffff0000, v149
	v_addc_co_u32_e32 v167, vcc, -1, v167, vcc
	v_lshlrev_b32_e32 v148, 16, v150
	v_and_b32_e32 v149, 0xffff0000, v150
	v_lshlrev_b32_e32 v150, 16, v151
	v_and_b32_e32 v151, 0xffff0000, v151
	global_store_dwordx4 v[166:167], v[158:161], off offset:-1024 sc1
	global_store_dwordx4 v[166:167], v[148:151], off offset:-1008 sc1

; __device__ __forceinline__ u32x4 pack8(f32x4 v0, f32x4 v1) { u32x4 w; w.x = cvt_pk_bf16(v0[0], v0[1]); w.y = cvt_pk_bf16(v0[2], v0[3]); w.z = cvt_pk_bf16(v1[0], v1[1]); w.w = cvt_pk_bf16(v1[2], v1[3]); return w; }
; __device__ __forceinline__ void unpack8(u32x4 w, f32x4& v0, f32x4& v1) { v0 = (f32x4){bflo(w.x), bfhi(w.x), bflo(w.y), bfhi(w.y)}; v1 = (f32x4){bflo(w.z), bfhi(w.z), bflo(w.w), bfhi(w.w)}; }
;     __device__ __forceinline__ void operator()(const f32x4 (&acc)[2][2][4][2], const Unit& u, int wr, int wc, int fr_in, int fq_in) const {
;     ...
;             for (int m = 0; m < 4; ++m) { const int row = row0 + ai * HALF + m * 16; bf16_t* rowp = pbase + (size_t)(ai * HALF + m * 16) * NPJ;
; #pragma unroll
;                 for (int bj = 0; bj < 2; ++bj) { f32x4 v0 = acc[ai][bj][m][0] + bv[bj][0], v1 = acc[ai][bj][m][1] + bv[bj][1];
;                     if (isg) { v0 = sigmoid4(v0); v1 = sigmoid4(v1); }
;                     const u32x4 w = pack8(v0, v1); store16_wt(rowp + bj * HALF, w);
;                     if (isv) { const bool smp = row >= 8192; const int t = smp ? ((row - 8192) & 63) : (row & 2047); const int bb = smp ? ((row - 8192) >> 6) : (row >> 11);
;                         if (smp || t >= 1920) { float* d = out + (smp ? o_sv + ((size_t)(l * 16 + bb) * 128 + 64 + t) * 256 : o_pv + ((size_t)(l * 4 + bb) * 128 + (t - 1920)) * 256) + (col0 - 2304) + bj * HALF;
;                             f32x4 r0, r1; unpack8(w, r0, r1); *(f32x4*)(d) = r0; *(f32x4*)(d + 4) = r1; } } } }
.LBB0_356:
	v_cvt_pk_bf16_f32 v150, v150, v151
	v_cvt_pk_bf16_f32 v151, v158, v159
	v_add_co_u32_e32 v158, vcc, 0x9c000, v154
	v_cvt_pk_bf16_f32 v148, v148, v149
	v_cvt_pk_bf16_f32 v149, v160, v161
	v_addc_co_u32_e32 v159, vcc, 0, v155, vcc
	global_store_dwordx4 v[158:159], v[148:151], off offset:256 sc1
	s_and_saveexec_b64 s[58:59], s[42:43]
	s_cbranch_execz .LBB0_362
	s_and_saveexec_b64 s[0:1], s[40:41]
	s_xor_b64 s[40:41], exec, s[0:1]
	v_add_u32_e32 v156, s31, v164
	v_mov_b32_e32 v157, v98
	v_lshlrev_b64 v[156:157], 15, v[156:157]
	v_or_b32_e32 v156, v156, v165
	s_mov_b64 s[0:1], 0x1520000
	v_lshl_add_u64 v[158:159], v[156:157], 0, s[0:1]
	s_andn2_saveexec_b64 s[40:41], s[40:41]
	v_add_u32_e32 v158, s75, v163
	v_ashrrev_i32_e32 v159, 31, v158
	v_lshlrev_b64 v[158:159], 15, v[158:159]
	v_lshl_add_u64 v[156:157], v[156:157], 0, v[158:159]
	s_mov_b64 s[0:1], 0x1280000
	v_lshl_add_u64 v[158:159], v[156:157], 0, s[0:1]
	s_or_b64 exec, exec, s[40:41]
	v_lshl_add_u64 v[156:157], v[158:159], 2, s[64:65]
	v_lshl_add_u64 v[160:161], v[152:153], 2, v[156:157]
	v_add_co_u32_e32 v160, vcc, 0xffffe000, v160
	v_lshlrev_b32_e32 v156, 16, v148
	v_and_b32_e32 v157, 0xffff0000, v148
	v_lshlrev_b32_e32 v158, 16, v149
	v_and_b32_e32 v159, 0xffff0000, v149
	v_addc_co_u32_e32 v161, vcc, -1, v161, vcc
	v_lshlrev_b32_e32 v148, 16, v150
	v_and_b32_e32 v149, 0xffff0000, v150
	v_lshlrev_b32_e32 v150, 16, v151
	v_and_b32_e32 v151, 0xffff0000, v151
	global_store_dwordx4 v[160:161], v[156:159], off offset:-512 sc1
	global_store_dwordx4 v[160:161], v[148:151], off offset:-496 sc1

; __device__ __forceinline__ u32x4 pack8(f32x4 v0, f32x4 v1) { u32x4 w; w.x = cvt_pk_bf16(v0[0], v0[1]); w.y = cvt_pk_bf16(v0[2], v0[3]); w.z = cvt_pk_bf16(v1[0], v1[1]); w.w = cvt_pk_bf16(v1[2], v1[3]); return w; }
; __device__ __forceinline__ void unpack8(u32x4 w, f32x4& v0, f32x4& v1) { v0 = (f32x4){bflo(w.x), bfhi(w.x), bflo(w.y), bfhi(w.y)}; v1 = (f32x4){bflo(w.z), bfhi(w.z), bflo(w.w), bfhi(w.w)}; }
;     __device__ __forceinline__ void operator()(const f32x4 (&acc)[2][2][4][2], const Unit& u, int wr, int wc, int fr_in, int fq_in) const {
;     ...
;             for (int m = 0; m < 4; ++m) { const int row = row0 + ai * HALF + m * 16; bf16_t* rowp = pbase + (size_t)(ai * HALF + m * 16) * NPJ;
; #pragma unroll
;                 for (int bj = 0; bj < 2; ++bj) { f32x4 v0 = acc[ai][bj][m][0] + bv[bj][0], v1 = acc[ai][bj][m][1] + bv[bj][1];
;                     if (isg) { v0 = sigmoid4(v0); v1 = sigmoid4(v1); }
;                     const u32x4 w = pack8(v0, v1); store16_wt(rowp + bj * HALF, w);
;                     if (isv) { const bool smp = row >= 8192; const int t = smp ? ((row - 8192) & 63) : (row & 2047); const int bb = smp ? ((row - 8192) >> 6) : (row >> 11);
;                         if (smp || t >= 1920) { float* d = out + (smp ? o_sv + ((size_t)(l * 16 + bb) * 128 + 64 + t) * 256 : o_pv + ((size_t)(l * 4 + bb) * 128 + (t - 1920)) * 256) + (col0 - 2304) + bj * HALF;
;                             f32x4 r0, r1; unpack8(w, r0, r1); *(f32x4*)(d) = r0; *(f32x4*)(d + 4) = r1; } } } }
.LBB0_366:
	v_add_u32_e32 v156, 0x80, v192
	s_movk_i32 s0, 0x1f7f
	v_cmp_lt_i32_e64 s[40:41], s0, v192
	s_movk_i32 s0, 0x1f80
	v_and_b32_e32 v157, 0x7ff, v156
	v_add_u32_e32 v163, 0xffffe080, v192
	v_cmp_gt_i32_e64 s[42:43], s0, v192
	v_lshrrev_b32_e32 v164, 6, v163
	v_ashrrev_i32_e32 v163, 11, v156
	v_subrev_co_u32_e32 v156, vcc, 0x780, v157
	s_and_b64 s[0:1], s[42:43], vcc
	v_ashrrev_i32_e32 v157, 31, v156
	v_cvt_pk_bf16_f32 v150, v150, v151
	v_cvt_pk_bf16_f32 v151, v158, v159
	v_add_co_u32_e32 v158, vcc, 0x1a0000, v154
	v_lshlrev_b64 v[156:157], 8, v[156:157]
	v_cvt_pk_bf16_f32 v148, v148, v149
	v_cvt_pk_bf16_f32 v149, v160, v161
	v_addc_co_u32_e32 v159, vcc, 0, v155, vcc
	s_nor_b64 s[42:43], s[56:57], s[0:1]
	global_store_dwordx4 v[158:159], v[148:151], off sc1
	s_and_saveexec_b64 s[58:59], s[42:43]
	s_cbranch_execz .LBB0_372
	s_and_saveexec_b64 s[0:1], s[40:41]
	s_xor_b64 s[60:61], exec, s[0:1]
	v_add_u32_e32 v158, s31, v164
	v_mov_b32_e32 v159, v98
	v_lshlrev_b64 v[158:159], 15, v[158:159]
	v_or_b32_e32 v158, v158, v162
	s_mov_b64 s[0:1], 0x1520000
	v_lshl_add_u64 v[158:159], v[158:159], 0, s[0:1]
	s_andn2_saveexec_b64 s[60:61], s[60:61]
	v_add_u32_e32 v158, s75, v163
	v_ashrrev_i32_e32 v159, 31, v158
	v_lshlrev_b64 v[158:159], 15, v[158:159]
	v_lshl_add_u64 v[158:159], v[156:157], 0, v[158:159]
	s_mov_b64 s[0:1], 0x1280000
	v_lshl_add_u64 v[158:159], v[158:159], 0, s[0:1]
	s_or_b64 exec, exec, s[60:61]
	v_readlane_b32 s60, v251, 14
	v_readlane_b32 s64, v251, 18
	v_readlane_b32 s65, v251, 19
	v_readlane_b32 s61, v251, 15
	v_readlane_b32 s62, v251, 16
	v_lshl_add_u64 v[158:159], v[158:159], 2, s[64:65]
	v_lshl_add_u64 v[166:167], v[152:153], 2, v[158:159]
	v_add_co_u32_e32 v166, vcc, 0xffffe000, v166
	v_readlane_b32 s63, v251, 17
	v_readlane_b32 s66, v251, 20
	v_readlane_b32 s67, v251, 21
	v_lshlrev_b32_e32 v158, 16, v148
	v_and_b32_e32 v159, 0xffff0000, v148
	v_lshlrev_b32_e32 v160, 16, v149
	v_and_b32_e32 v161, 0xffff0000, v149
	v_addc_co_u32_e32 v167, vcc, -1, v167, vcc
	v_lshlrev_b32_e32 v148, 16, v150
	v_and_b32_e32 v149, 0xffff0000, v150
	v_lshlrev_b32_e32 v150, 16, v151
	v_and_b32_e32 v151, 0xffff0000, v151
	global_store_dwordx4 v[166:167], v[158:161], off offset:-1024 sc1
	global_store_dwordx4 v[166:167], v[148:151], off offset:-1008 sc1

; __device__ __forceinline__ u32x4 pack8(f32x4 v0, f32x4 v1) { u32x4 w; w.x = cvt_pk_bf16(v0[0], v0[1]); w.y = cvt_pk_bf16(v0[2], v0[3]); w.z = cvt_pk_bf16(v1[0], v1[1]); w.w = cvt_pk_bf16(v1[2], v1[3]); return w; }
; __device__ __forceinline__ void unpack8(u32x4 w, f32x4& v0, f32x4& v1) { v0 = (f32x4){bflo(w.x), bfhi(w.x), bflo(w.y), bfhi(w.y)}; v1 = (f32x4){bflo(w.z), bfhi(w.z), bflo(w.w), bfhi(w.w)}; }
;     __device__ __forceinline__ void operator()(const f32x4 (&acc)[2][2][4][2], const Unit& u, int wr, int wc, int fr_in, int fq_in) const {
;     ...
;             for (int m = 0; m < 4; ++m) { const int row = row0 + ai * HALF + m * 16; bf16_t* rowp = pbase + (size_t)(ai * HALF + m * 16) * NPJ;
; #pragma unroll
;                 for (int bj = 0; bj < 2; ++bj) { f32x4 v0 = acc[ai][bj][m][0] + bv[bj][0], v1 = acc[ai][bj][m][1] + bv[bj][1];
;                     if (isg) { v0 = sigmoid4(v0); v1 = sigmoid4(v1); }
;                     const u32x4 w = pack8(v0, v1); store16_wt(rowp + bj * HALF, w);
;                     if (isv) { const bool smp = row >= 8192; const int t = smp ? ((row - 8192) & 63) : (row & 2047); const int bb = smp ? ((row - 8192) >> 6) : (row >> 11);
;                         if (smp || t >= 1920) { float* d = out + (smp ? o_sv + ((size_t)(l * 16 + bb) * 128 + 64 + t) * 256 : o_pv + ((size_t)(l * 4 + bb) * 128 + (t - 1920)) * 256) + (col0 - 2304) + bj * HALF;
;                             f32x4 r0, r1; unpack8(w, r0, r1); *(f32x4*)(d) = r0; *(f32x4*)(d + 4) = r1; } } } }
.LBB0_376:
	v_cvt_pk_bf16_f32 v150, v150, v151
	v_cvt_pk_bf16_f32 v151, v158, v159
	v_add_co_u32_e32 v158, vcc, 0x1a0000, v154
	v_cvt_pk_bf16_f32 v148, v148, v149
	v_cvt_pk_bf16_f32 v149, v160, v161
	v_addc_co_u32_e32 v159, vcc, 0, v155, vcc
	global_store_dwordx4 v[158:159], v[148:151], off offset:256 sc1
	s_and_saveexec_b64 s[58:59], s[42:43]
	s_cbranch_execz .LBB0_382
	s_and_saveexec_b64 s[0:1], s[40:41]
	s_xor_b64 s[40:41], exec, s[0:1]
	v_add_u32_e32 v156, s31, v164
	v_mov_b32_e32 v157, v98
	v_lshlrev_b64 v[156:157], 15, v[156:157]
	v_or_b32_e32 v156, v156, v162
	s_mov_b64 s[0:1], 0x1520000
	v_lshl_add_u64 v[158:159], v[156:157], 0, s[0:1]
	s_andn2_saveexec_b64 s[40:41], s[40:41]
	v_add_u32_e32 v158, s75, v163
	v_ashrrev_i32_e32 v159, 31, v158
	v_lshlrev_b64 v[158:159], 15, v[158:159]
	v_lshl_add_u64 v[156:157], v[156:157], 0, v[158:159]
	s_mov_b64 s[0:1], 0x1280000
	v_lshl_add_u64 v[158:159], v[156:157], 0, s[0:1]
	s_or_b64 exec, exec, s[40:41]
	v_lshl_add_u64 v[156:157], v[158:159], 2, s[64:65]
	v_lshl_add_u64 v[160:161], v[152:153], 2, v[156:157]
	v_add_co_u32_e32 v160, vcc, 0xffffe000, v160
	v_lshlrev_b32_e32 v156, 16, v148
	v_and_b32_e32 v157, 0xffff0000, v148
	v_lshlrev_b32_e32 v158, 16, v149
	v_and_b32_e32 v159, 0xffff0000, v149
	v_addc_co_u32_e32 v161, vcc, -1, v161, vcc
	v_lshlrev_b32_e32 v148, 16, v150
	v_and_b32_e32 v149, 0xffff0000, v150
	v_lshlrev_b32_e32 v150, 16, v151
	v_and_b32_e32 v151, 0xffff0000, v151
	global_store_dwordx4 v[160:161], v[156:159], off offset:-512 sc1
	global_store_dwordx4 v[160:161], v[148:151], off offset:-496 sc1

; __device__ __forceinline__ u32x4 pack8(f32x4 v0, f32x4 v1) { u32x4 w; w.x = cvt_pk_bf16(v0[0], v0[1]); w.y = cvt_pk_bf16(v0[2], v0[3]); w.z = cvt_pk_bf16(v1[0], v1[1]); w.w = cvt_pk_bf16(v1[2], v1[3]); return w; }
; __device__ __forceinline__ void unpack8(u32x4 w, f32x4& v0, f32x4& v1) { v0 = (f32x4){bflo(w.x), bfhi(w.x), bflo(w.y), bfhi(w.y)}; v1 = (f32x4){bflo(w.z), bfhi(w.z), bflo(w.w), bfhi(w.w)}; }
;     __device__ __forceinline__ void operator()(const f32x4 (&acc)[2][2][4][2], const Unit& u, int wr, int wc, int fr_in, int fq_in) const {
;     ...
;             for (int m = 0; m < 4; ++m) { const int row = row0 + ai * HALF + m * 16; bf16_t* rowp = pbase + (size_t)(ai * HALF + m * 16) * NPJ;
; #pragma unroll
;                 for (int bj = 0; bj < 2; ++bj) { f32x4 v0 = acc[ai][bj][m][0] + bv[bj][0], v1 = acc[ai][bj][m][1] + bv[bj][1];
;                     if (isg) { v0 = sigmoid4(v0); v1 = sigmoid4(v1); }
;                     const u32x4 w = pack8(v0, v1); store16_wt(rowp + bj * HALF, w);
;                     if (isv) { const bool smp = row >= 8192; const int t = smp ? ((row - 8192) & 63) : (row & 2047); const int bb = smp ? ((row - 8192) >> 6) : (row >> 11);
;                         if (smp || t >= 1920) { float* d = out + (smp ? o_sv + ((size_t)(l * 16 + bb) * 128 + 64 + t) * 256 : o_pv + ((size_t)(l * 4 + bb) * 128 + (t - 1920)) * 256) + (col0 - 2304) + bj * HALF;
;                             f32x4 r0, r1; unpack8(w, r0, r1); *(f32x4*)(d) = r0; *(f32x4*)(d + 4) = r1; } } } }
.LBB0_386:
	v_add_u32_e32 v164, 0x90, v192
	s_movk_i32 s0, 0x1f6f
	v_cmp_lt_i32_e64 s[40:41], s0, v192
	s_movk_i32 s0, 0x1f70
	v_and_b32_e32 v156, 0x7ff, v164
	v_cmp_gt_i32_e64 s[42:43], s0, v192
	v_add_u32_e32 v157, 0xffffe090, v192
	v_ashrrev_i32_e32 v162, 11, v164
	v_subrev_co_u32_e32 v156, vcc, 0x780, v156
	v_lshlrev_b32_e32 v164, 8, v164
	v_lshrrev_b32_e32 v163, 6, v157
	s_and_b64 s[0:1], s[42:43], vcc
	v_ashrrev_i32_e32 v157, 31, v156
	v_and_b32_e32 v164, 0x3f00, v164
	v_cvt_pk_bf16_f32 v150, v150, v151
	v_cvt_pk_bf16_f32 v151, v158, v159
	v_add_co_u32_e32 v158, vcc, 0x1d4000, v154
	v_lshlrev_b64 v[156:157], 8, v[156:157]
	v_or_b32_e32 v164, 0x4000, v164
	v_cvt_pk_bf16_f32 v148, v148, v149
	v_cvt_pk_bf16_f32 v149, v160, v161
	v_addc_co_u32_e32 v159, vcc, 0, v155, vcc
	s_nor_b64 s[42:43], s[56:57], s[0:1]
	global_store_dwordx4 v[158:159], v[148:151], off sc1
	s_and_saveexec_b64 s[58:59], s[42:43]
	s_cbranch_execz .LBB0_392
	s_and_saveexec_b64 s[0:1], s[40:41]
	s_xor_b64 s[60:61], exec, s[0:1]
	v_add_u32_e32 v158, s31, v163
	v_mov_b32_e32 v159, v98
	v_lshlrev_b64 v[158:159], 15, v[158:159]
	v_or_b32_e32 v158, v158, v164
	s_mov_b64 s[0:1], 0x1520000
	v_lshl_add_u64 v[158:159], v[158:159], 0, s[0:1]
	s_andn2_saveexec_b64 s[60:61], s[60:61]
	v_add_u32_e32 v158, s75, v162
	v_ashrrev_i32_e32 v159, 31, v158
	v_lshlrev_b64 v[158:159], 15, v[158:159]
	v_lshl_add_u64 v[158:159], v[156:157], 0, v[158:159]
	s_mov_b64 s[0:1], 0x1280000
	v_lshl_add_u64 v[158:159], v[158:159], 0, s[0:1]
	s_or_b64 exec, exec, s[60:61]
	v_readlane_b32 s60, v251, 14
	v_readlane_b32 s64, v251, 18
	v_readlane_b32 s65, v251, 19
	v_readlane_b32 s61, v251, 15
	v_readlane_b32 s62, v251, 16
	v_lshl_add_u64 v[158:159], v[158:159], 2, s[64:65]
	v_lshl_add_u64 v[166:167], v[152:153], 2, v[158:159]
	v_add_co_u32_e32 v166, vcc, 0xffffe000, v166
	v_readlane_b32 s63, v251, 17
	v_readlane_b32 s66, v251, 20
	v_readlane_b32 s67, v251, 21
	v_lshlrev_b32_e32 v158, 16, v148
	v_and_b32_e32 v159, 0xffff0000, v148
	v_lshlrev_b32_e32 v160, 16, v149
	v_and_b32_e32 v161, 0xffff0000, v149
	v_addc_co_u32_e32 v167, vcc, -1, v167, vcc
	v_lshlrev_b32_e32 v148, 16, v150
	v_and_b32_e32 v149, 0xffff0000, v150
	v_lshlrev_b32_e32 v150, 16, v151
	v_and_b32_e32 v151, 0xffff0000, v151
	global_store_dwordx4 v[166:167], v[158:161], off offset:-1024 sc1
	global_store_dwordx4 v[166:167], v[148:151], off offset:-1008 sc1

; __device__ __forceinline__ u32x4 pack8(f32x4 v0, f32x4 v1) { u32x4 w; w.x = cvt_pk_bf16(v0[0], v0[1]); w.y = cvt_pk_bf16(v0[2], v0[3]); w.z = cvt_pk_bf16(v1[0], v1[1]); w.w = cvt_pk_bf16(v1[2], v1[3]); return w; }
; __device__ __forceinline__ void unpack8(u32x4 w, f32x4& v0, f32x4& v1) { v0 = (f32x4){bflo(w.x), bfhi(w.x), bflo(w.y), bfhi(w.y)}; v1 = (f32x4){bflo(w.z), bfhi(w.z), bflo(w.w), bfhi(w.w)}; }
;     __device__ __forceinline__ void operator()(const f32x4 (&acc)[2][2][4][2], const Unit& u, int wr, int wc, int fr_in, int fq_in) const {
;     ...
;             for (int m = 0; m < 4; ++m) { const int row = row0 + ai * HALF + m * 16; bf16_t* rowp = pbase + (size_t)(ai * HALF + m * 16) * NPJ;
; #pragma unroll
;                 for (int bj = 0; bj < 2; ++bj) { f32x4 v0 = acc[ai][bj][m][0] + bv[bj][0], v1 = acc[ai][bj][m][1] + bv[bj][1];
;                     if (isg) { v0 = sigmoid4(v0); v1 = sigmoid4(v1); }
;                     const u32x4 w = pack8(v0, v1); store16_wt(rowp + bj * HALF, w);
;                     if (isv) { const bool smp = row >= 8192; const int t = smp ? ((row - 8192) & 63) : (row & 2047); const int bb = smp ? ((row - 8192) >> 6) : (row >> 11);
;                         if (smp || t >= 1920) { float* d = out + (smp ? o_sv + ((size_t)(l * 16 + bb) * 128 + 64 + t) * 256 : o_pv + ((size_t)(l * 4 + bb) * 128 + (t - 1920)) * 256) + (col0 - 2304) + bj * HALF;
;                             f32x4 r0, r1; unpack8(w, r0, r1); *(f32x4*)(d) = r0; *(f32x4*)(d + 4) = r1; } } } }
.LBB0_396:
	v_cvt_pk_bf16_f32 v150, v150, v151
	v_cvt_pk_bf16_f32 v151, v158, v159
	v_add_co_u32_e32 v158, vcc, 0x1d4000, v154
	v_cvt_pk_bf16_f32 v148, v148, v149
	v_cvt_pk_bf16_f32 v149, v160, v161
	v_addc_co_u32_e32 v159, vcc, 0, v155, vcc
	global_store_dwordx4 v[158:159], v[148:151], off offset:256 sc1
	s_and_saveexec_b64 s[58:59], s[42:43]
	s_cbranch_execz .LBB0_402
	s_and_saveexec_b64 s[0:1], s[40:41]
	s_xor_b64 s[40:41], exec, s[0:1]
	v_add_u32_e32 v156, s31, v163
	v_mov_b32_e32 v157, v98
	v_lshlrev_b64 v[156:157], 15, v[156:157]
	v_or_b32_e32 v156, v156, v164
	s_mov_b64 s[0:1], 0x1520000
	v_lshl_add_u64 v[158:159], v[156:157], 0, s[0:1]
	s_andn2_saveexec_b64 s[40:41], s[40:41]
	v_add_u32_e32 v158, s75, v162
	v_ashrrev_i32_e32 v159, 31, v158
	v_lshlrev_b64 v[158:159], 15, v[158:159]
	v_lshl_add_u64 v[156:157], v[156:157], 0, v[158:159]
	s_mov_b64 s[0:1], 0x1280000
	v_lshl_add_u64 v[158:159], v[156:157], 0, s[0:1]
	s_or_b64 exec, exec, s[40:41]
	v_lshl_add_u64 v[156:157], v[158:159], 2, s[64:65]
	v_lshl_add_u64 v[160:161], v[152:153], 2, v[156:157]
	v_add_co_u32_e32 v160, vcc, 0xffffe000, v160
	v_lshlrev_b32_e32 v156, 16, v148
	v_and_b32_e32 v157, 0xffff0000, v148
	v_lshlrev_b32_e32 v158, 16, v149
	v_and_b32_e32 v159, 0xffff0000, v149
	v_addc_co_u32_e32 v161, vcc, -1, v161, vcc
	v_lshlrev_b32_e32 v148, 16, v150
	v_and_b32_e32 v149, 0xffff0000, v150
	v_lshlrev_b32_e32 v150, 16, v151
	v_and_b32_e32 v151, 0xffff0000, v151
	global_store_dwordx4 v[160:161], v[156:159], off offset:-512 sc1
	global_store_dwordx4 v[160:161], v[148:151], off offset:-496 sc1

; __device__ __forceinline__ u32x4 pack8(f32x4 v0, f32x4 v1) { u32x4 w; w.x = cvt_pk_bf16(v0[0], v0[1]); w.y = cvt_pk_bf16(v0[2], v0[3]); w.z = cvt_pk_bf16(v1[0], v1[1]); w.w = cvt_pk_bf16(v1[2], v1[3]); return w; }
; __device__ __forceinline__ void unpack8(u32x4 w, f32x4& v0, f32x4& v1) { v0 = (f32x4){bflo(w.x), bfhi(w.x), bflo(w.y), bfhi(w.y)}; v1 = (f32x4){bflo(w.z), bfhi(w.z), bflo(w.w), bfhi(w.w)}; }
;     __device__ __forceinline__ void operator()(const f32x4 (&acc)[2][2][4][2], const Unit& u, int wr, int wc, int fr_in, int fq_in) const {
;     ...
;             for (int m = 0; m < 4; ++m) { const int row = row0 + ai * HALF + m * 16; bf16_t* rowp = pbase + (size_t)(ai * HALF + m * 16) * NPJ;
; #pragma unroll
;                 for (int bj = 0; bj < 2; ++bj) { f32x4 v0 = acc[ai][bj][m][0] + bv[bj][0], v1 = acc[ai][bj][m][1] + bv[bj][1];
;                     if (isg) { v0 = sigmoid4(v0); v1 = sigmoid4(v1); }
;                     const u32x4 w = pack8(v0, v1); store16_wt(rowp + bj * HALF, w);
;                     if (isv) { const bool smp = row >= 8192; const int t = smp ? ((row - 8192) & 63) : (row & 2047); const int bb = smp ? ((row - 8192) >> 6) : (row >> 11);
;                         if (smp || t >= 1920) { float* d = out + (smp ? o_sv + ((size_t)(l * 16 + bb) * 128 + 64 + t) * 256 : o_pv + ((size_t)(l * 4 + bb) * 128 + (t - 1920)) * 256) + (col0 - 2304) + bj * HALF;
;                             f32x4 r0, r1; unpack8(w, r0, r1); *(f32x4*)(d) = r0; *(f32x4*)(d + 4) = r1; } } } }
.LBB0_406:
	v_add_u32_e32 v164, 0xa0, v192
	s_movk_i32 s0, 0x1f5f
	v_cmp_lt_i32_e64 s[40:41], s0, v192
	s_movk_i32 s0, 0x1f60
	v_and_b32_e32 v156, 0x7ff, v164
	v_cmp_gt_i32_e64 s[42:43], s0, v192
	v_add_u32_e32 v157, 0xffffe0a0, v192
	v_ashrrev_i32_e32 v162, 11, v164
	v_subrev_co_u32_e32 v156, vcc, 0x780, v156
	v_lshlrev_b32_e32 v164, 8, v164
	v_lshrrev_b32_e32 v163, 6, v157
	s_and_b64 s[0:1], s[42:43], vcc
	v_ashrrev_i32_e32 v157, 31, v156
	v_and_b32_e32 v164, 0x3f00, v164
	v_cvt_pk_bf16_f32 v150, v150, v151
	v_cvt_pk_bf16_f32 v151, v158, v159
	v_add_co_u32_e32 v158, vcc, 0x208000, v154
	v_lshlrev_b64 v[156:157], 8, v[156:157]
	v_or_b32_e32 v164, 0x4000, v164
	v_cvt_pk_bf16_f32 v148, v148, v149
	v_cvt_pk_bf16_f32 v149, v160, v161
	v_addc_co_u32_e32 v159, vcc, 0, v155, vcc
	s_nor_b64 s[42:43], s[56:57], s[0:1]
	global_store_dwordx4 v[158:159], v[148:151], off sc1
	s_and_saveexec_b64 s[58:59], s[42:43]
	s_cbranch_execz .LBB0_412
	s_and_saveexec_b64 s[0:1], s[40:41]
	s_xor_b64 s[60:61], exec, s[0:1]
	v_add_u32_e32 v158, s31, v163
	v_mov_b32_e32 v159, v98
	v_lshlrev_b64 v[158:159], 15, v[158:159]
	v_or_b32_e32 v158, v158, v164
	s_mov_b64 s[0:1], 0x1520000
	v_lshl_add_u64 v[158:159], v[158:159], 0, s[0:1]
	s_andn2_saveexec_b64 s[60:61], s[60:61]
	v_add_u32_e32 v158, s75, v162
	v_ashrrev_i32_e32 v159, 31, v158
	v_lshlrev_b64 v[158:159], 15, v[158:159]
	v_lshl_add_u64 v[158:159], v[156:157], 0, v[158:159]
	s_mov_b64 s[0:1], 0x1280000
	v_lshl_add_u64 v[158:159], v[158:159], 0, s[0:1]
	s_or_b64 exec, exec, s[60:61]
	v_readlane_b32 s60, v251, 14
	v_readlane_b32 s64, v251, 18
	v_readlane_b32 s65, v251, 19
	v_readlane_b32 s61, v251, 15
	v_readlane_b32 s62, v251, 16
	v_lshl_add_u64 v[158:159], v[158:159], 2, s[64:65]
	v_lshl_add_u64 v[166:167], v[152:153], 2, v[158:159]
	v_add_co_u32_e32 v166, vcc, 0xffffe000, v166
	v_readlane_b32 s63, v251, 17
	v_readlane_b32 s66, v251, 20
	v_readlane_b32 s67, v251, 21
	v_lshlrev_b32_e32 v158, 16, v148
	v_and_b32_e32 v159, 0xffff0000, v148
	v_lshlrev_b32_e32 v160, 16, v149
	v_and_b32_e32 v161, 0xffff0000, v149
	v_addc_co_u32_e32 v167, vcc, -1, v167, vcc
	v_lshlrev_b32_e32 v148, 16, v150
	v_and_b32_e32 v149, 0xffff0000, v150
	v_lshlrev_b32_e32 v150, 16, v151
	v_and_b32_e32 v151, 0xffff0000, v151
	global_store_dwordx4 v[166:167], v[158:161], off offset:-1024 sc1
	global_store_dwordx4 v[166:167], v[148:151], off offset:-1008 sc1

; __device__ __forceinline__ u32x4 pack8(f32x4 v0, f32x4 v1) { u32x4 w; w.x = cvt_pk_bf16(v0[0], v0[1]); w.y = cvt_pk_bf16(v0[2], v0[3]); w.z = cvt_pk_bf16(v1[0], v1[1]); w.w = cvt_pk_bf16(v1[2], v1[3]); return w; }
; __device__ __forceinline__ void unpack8(u32x4 w, f32x4& v0, f32x4& v1) { v0 = (f32x4){bflo(w.x), bfhi(w.x), bflo(w.y), bfhi(w.y)}; v1 = (f32x4){bflo(w.z), bfhi(w.z), bflo(w.w), bfhi(w.w)}; }
;     __device__ __forceinline__ void operator()(const f32x4 (&acc)[2][2][4][2], const Unit& u, int wr, int wc, int fr_in, int fq_in) const {
;     ...
;             for (int m = 0; m < 4; ++m) { const int row = row0 + ai * HALF + m * 16; bf16_t* rowp = pbase + (size_t)(ai * HALF + m * 16) * NPJ;
; #pragma unroll
;                 for (int bj = 0; bj < 2; ++bj) { f32x4 v0 = acc[ai][bj][m][0] + bv[bj][0], v1 = acc[ai][bj][m][1] + bv[bj][1];
;                     if (isg) { v0 = sigmoid4(v0); v1 = sigmoid4(v1); }
;                     const u32x4 w = pack8(v0, v1); store16_wt(rowp + bj * HALF, w);
;                     if (isv) { const bool smp = row >= 8192; const int t = smp ? ((row - 8192) & 63) : (row & 2047); const int bb = smp ? ((row - 8192) >> 6) : (row >> 11);
;                         if (smp || t >= 1920) { float* d = out + (smp ? o_sv + ((size_t)(l * 16 + bb) * 128 + 64 + t) * 256 : o_pv + ((size_t)(l * 4 + bb) * 128 + (t - 1920)) * 256) + (col0 - 2304) + bj * HALF;
;                             f32x4 r0, r1; unpack8(w, r0, r1); *(f32x4*)(d) = r0; *(f32x4*)(d + 4) = r1; } } } }
.LBB0_416:
	v_cvt_pk_bf16_f32 v150, v150, v151
	v_cvt_pk_bf16_f32 v151, v158, v159
	v_add_co_u32_e32 v158, vcc, 0x208000, v154
	v_cvt_pk_bf16_f32 v148, v148, v149
	v_cvt_pk_bf16_f32 v149, v160, v161
	v_addc_co_u32_e32 v159, vcc, 0, v155, vcc
	global_store_dwordx4 v[158:159], v[148:151], off offset:256 sc1
	s_and_saveexec_b64 s[58:59], s[42:43]
	s_cbranch_execz .LBB0_422
	s_and_saveexec_b64 s[0:1], s[40:41]
	s_xor_b64 s[40:41], exec, s[0:1]
	v_add_u32_e32 v156, s31, v163
	v_mov_b32_e32 v157, v98
	v_lshlrev_b64 v[156:157], 15, v[156:157]
	v_or_b32_e32 v156, v156, v164
	s_mov_b64 s[0:1], 0x1520000
	v_lshl_add_u64 v[158:159], v[156:157], 0, s[0:1]
	s_andn2_saveexec_b64 s[40:41], s[40:41]
	v_add_u32_e32 v158, s75, v162
	v_ashrrev_i32_e32 v159, 31, v158
	v_lshlrev_b64 v[158:159], 15, v[158:159]
	v_lshl_add_u64 v[156:157], v[156:157], 0, v[158:159]
	s_mov_b64 s[0:1], 0x1280000
	v_lshl_add_u64 v[158:159], v[156:157], 0, s[0:1]
	s_or_b64 exec, exec, s[40:41]
	v_lshl_add_u64 v[156:157], v[158:159], 2, s[64:65]
	v_lshl_add_u64 v[160:161], v[152:153], 2, v[156:157]
	v_add_co_u32_e32 v160, vcc, 0xffffe000, v160
	v_lshlrev_b32_e32 v156, 16, v148
	v_and_b32_e32 v157, 0xffff0000, v148
	v_lshlrev_b32_e32 v158, 16, v149
	v_and_b32_e32 v159, 0xffff0000, v149
	v_addc_co_u32_e32 v161, vcc, -1, v161, vcc
	v_lshlrev_b32_e32 v148, 16, v150
	v_and_b32_e32 v149, 0xffff0000, v150
	v_lshlrev_b32_e32 v150, 16, v151
	v_and_b32_e32 v151, 0xffff0000, v151
	global_store_dwordx4 v[160:161], v[156:159], off offset:-512 sc1
	global_store_dwordx4 v[160:161], v[148:151], off offset:-496 sc1

; __device__ __forceinline__ u32x4 pack8(f32x4 v0, f32x4 v1) { u32x4 w; w.x = cvt_pk_bf16(v0[0], v0[1]); w.y = cvt_pk_bf16(v0[2], v0[3]); w.z = cvt_pk_bf16(v1[0], v1[1]); w.w = cvt_pk_bf16(v1[2], v1[3]); return w; }
; __device__ __forceinline__ void unpack8(u32x4 w, f32x4& v0, f32x4& v1) { v0 = (f32x4){bflo(w.x), bfhi(w.x), bflo(w.y), bfhi(w.y)}; v1 = (f32x4){bflo(w.z), bfhi(w.z), bflo(w.w), bfhi(w.w)}; }
;     __device__ __forceinline__ void operator()(const f32x4 (&acc)[2][2][4][2], const Unit& u, int wr, int wc, int fr_in, int fq_in) const {
;     ...
;             for (int m = 0; m < 4; ++m) { const int row = row0 + ai * HALF + m * 16; bf16_t* rowp = pbase + (size_t)(ai * HALF + m * 16) * NPJ;
; #pragma unroll
;                 for (int bj = 0; bj < 2; ++bj) { f32x4 v0 = acc[ai][bj][m][0] + bv[bj][0], v1 = acc[ai][bj][m][1] + bv[bj][1];
;                     if (isg) { v0 = sigmoid4(v0); v1 = sigmoid4(v1); }
;                     const u32x4 w = pack8(v0, v1); store16_wt(rowp + bj * HALF, w);
;                     if (isv) { const bool smp = row >= 8192; const int t = smp ? ((row - 8192) & 63) : (row & 2047); const int bb = smp ? ((row - 8192) >> 6) : (row >> 11);
;                         if (smp || t >= 1920) { float* d = out + (smp ? o_sv + ((size_t)(l * 16 + bb) * 128 + 64 + t) * 256 : o_pv + ((size_t)(l * 4 + bb) * 128 + (t - 1920)) * 256) + (col0 - 2304) + bj * HALF;
;                             f32x4 r0, r1; unpack8(w, r0, r1); *(f32x4*)(d) = r0; *(f32x4*)(d + 4) = r1; } } } }
.LBB0_426:
	v_add_u32_e32 v158, 0xb0, v192
	v_and_b32_e32 v140, 0x7ff, v158
	v_add_u32_e32 v141, 0xffffe0b0, v192
	v_subrev_co_u32_e32 v140, vcc, 0x780, v140
	s_movk_i32 s0, 0x1f4f
	v_lshrrev_b32_e32 v157, 6, v141
	v_ashrrev_i32_e32 v141, 31, v140
	v_cmp_lt_i32_e64 s[40:41], s0, v192
	s_movk_i32 s0, 0x1f50
	v_lshlrev_b64 v[144:145], 8, v[140:141]
	v_lshlrev_b32_e32 v140, 8, v158
	v_cmp_gt_i32_e64 s[42:43], s0, v192
	v_and_b32_e32 v140, 0x3f00, v140
	v_ashrrev_i32_e32 v156, 11, v158
	s_and_b64 s[0:1], s[42:43], vcc
	v_or_b32_e32 v158, 0x4000, v140
	v_cvt_pk_bf16_f32 v140, v146, v147
	v_add_co_u32_e32 v146, vcc, 0x23c000, v154
	v_cvt_pk_bf16_f32 v141, v150, v151
	v_cvt_pk_bf16_f32 v142, v142, v143
	v_cvt_pk_bf16_f32 v143, v148, v149
	v_addc_co_u32_e32 v147, vcc, 0, v155, vcc
	s_nor_b64 s[42:43], s[56:57], s[0:1]
	global_store_dwordx4 v[146:147], v[140:143], off sc1
	s_and_saveexec_b64 s[56:57], s[42:43]
	s_cbranch_execz .LBB0_432
	s_and_saveexec_b64 s[0:1], s[40:41]
	s_xor_b64 s[58:59], exec, s[0:1]
	v_add_u32_e32 v146, s31, v157
	v_mov_b32_e32 v147, v98
	v_lshlrev_b64 v[146:147], 15, v[146:147]
	v_or_b32_e32 v146, v146, v158
	s_mov_b64 s[0:1], 0x1520000
	v_lshl_add_u64 v[146:147], v[146:147], 0, s[0:1]
	s_andn2_saveexec_b64 s[58:59], s[58:59]
	v_add_u32_e32 v146, s75, v156
	v_ashrrev_i32_e32 v147, 31, v146
	v_lshlrev_b64 v[146:147], 15, v[146:147]
	v_lshl_add_u64 v[146:147], v[144:145], 0, v[146:147]
	s_mov_b64 s[0:1], 0x1280000
	v_lshl_add_u64 v[146:147], v[146:147], 0, s[0:1]
	s_or_b64 exec, exec, s[58:59]
	v_lshl_add_u64 v[146:147], v[146:147], 2, s[64:65]
	v_lshl_add_u64 v[150:151], v[152:153], 2, v[146:147]
	v_add_co_u32_e32 v150, vcc, 0xffffe000, v150
	v_lshlrev_b32_e32 v146, 16, v140
	v_and_b32_e32 v147, 0xffff0000, v140
	v_lshlrev_b32_e32 v148, 16, v141
	v_and_b32_e32 v149, 0xffff0000, v141
	v_addc_co_u32_e32 v151, vcc, -1, v151, vcc
	v_lshlrev_b32_e32 v140, 16, v142
	v_and_b32_e32 v141, 0xffff0000, v142
	v_lshlrev_b32_e32 v142, 16, v143
	v_and_b32_e32 v143, 0xffff0000, v143
	global_store_dwordx4 v[150:151], v[146:149], off offset:-1024 sc1
	global_store_dwordx4 v[150:151], v[140:143], off offset:-1008 sc1

; __device__ __forceinline__ u32x4 pack8(f32x4 v0, f32x4 v1) { u32x4 w; w.x = cvt_pk_bf16(v0[0], v0[1]); w.y = cvt_pk_bf16(v0[2], v0[3]); w.z = cvt_pk_bf16(v1[0], v1[1]); w.w = cvt_pk_bf16(v1[2], v1[3]); return w; }
; __device__ __forceinline__ void unpack8(u32x4 w, f32x4& v0, f32x4& v1) { v0 = (f32x4){bflo(w.x), bfhi(w.x), bflo(w.y), bfhi(w.y)}; v1 = (f32x4){bflo(w.z), bfhi(w.z), bflo(w.w), bfhi(w.w)}; }
;     __device__ __forceinline__ void operator()(const f32x4 (&acc)[2][2][4][2], const Unit& u, int wr, int wc, int fr_in, int fq_in) const {
;     ...
;             for (int m = 0; m < 4; ++m) { const int row = row0 + ai * HALF + m * 16; bf16_t* rowp = pbase + (size_t)(ai * HALF + m * 16) * NPJ;
; #pragma unroll
;                 for (int bj = 0; bj < 2; ++bj) { f32x4 v0 = acc[ai][bj][m][0] + bv[bj][0], v1 = acc[ai][bj][m][1] + bv[bj][1];
;                     if (isg) { v0 = sigmoid4(v0); v1 = sigmoid4(v1); }
;                     const u32x4 w = pack8(v0, v1); store16_wt(rowp + bj * HALF, w);
;                     if (isv) { const bool smp = row >= 8192; const int t = smp ? ((row - 8192) & 63) : (row & 2047); const int bb = smp ? ((row - 8192) >> 6) : (row >> 11);
;                         if (smp || t >= 1920) { float* d = out + (smp ? o_sv + ((size_t)(l * 16 + bb) * 128 + 64 + t) * 256 : o_pv + ((size_t)(l * 4 + bb) * 128 + (t - 1920)) * 256) + (col0 - 2304) + bj * HALF;
;                             f32x4 r0, r1; unpack8(w, r0, r1); *(f32x4*)(d) = r0; *(f32x4*)(d + 4) = r1; } } } }
.LBB0_436:
	v_cvt_pk_bf16_f32 v132, v136, v137
	v_add_co_u32_e32 v136, vcc, 0x23c000, v154
	v_cvt_pk_bf16_f32 v133, v140, v141
	v_cvt_pk_bf16_f32 v134, v134, v135
	v_cvt_pk_bf16_f32 v135, v138, v139
	v_addc_co_u32_e32 v137, vcc, 0, v155, vcc
	global_store_dwordx4 v[136:137], v[132:135], off offset:256 sc1
	s_and_saveexec_b64 s[38:39], s[42:43]
	s_cbranch_execz .LBB0_442
	s_and_saveexec_b64 s[0:1], s[40:41]
	s_xor_b64 s[40:41], exec, s[0:1]
	v_add_u32_e32 v136, s31, v157
	v_mov_b32_e32 v137, v98
	v_lshlrev_b64 v[136:137], 15, v[136:137]
	v_or_b32_e32 v136, v136, v158
	s_mov_b64 s[0:1], 0x1520000
	v_lshl_add_u64 v[136:137], v[136:137], 0, s[0:1]
	s_andn2_saveexec_b64 s[40:41], s[40:41]
	v_add_u32_e32 v136, s75, v156
	v_ashrrev_i32_e32 v137, 31, v136
	v_lshlrev_b64 v[136:137], 15, v[136:137]
	v_lshl_add_u64 v[136:137], v[144:145], 0, v[136:137]
	s_mov_b64 s[0:1], 0x1280000
	v_lshl_add_u64 v[136:137], v[136:137], 0, s[0:1]
	s_or_b64 exec, exec, s[40:41]
	v_lshl_add_u64 v[136:137], v[136:137], 2, s[64:65]
	v_lshl_add_u64 v[140:141], v[152:153], 2, v[136:137]
	v_add_co_u32_e32 v140, vcc, 0xffffe000, v140
	v_lshlrev_b32_e32 v136, 16, v132
	v_and_b32_e32 v137, 0xffff0000, v132
	v_lshlrev_b32_e32 v138, 16, v133
	v_and_b32_e32 v139, 0xffff0000, v133
	v_addc_co_u32_e32 v141, vcc, -1, v141, vcc
	v_lshlrev_b32_e32 v132, 16, v134
	v_and_b32_e32 v133, 0xffff0000, v134
	v_lshlrev_b32_e32 v134, 16, v135
	v_and_b32_e32 v135, 0xffff0000, v135
	global_store_dwordx4 v[140:141], v[136:139], off offset:-512 sc1
	global_store_dwordx4 v[140:141], v[132:135], off offset:-496 sc1

; #define GAS __attribute__((address_space(1)))
; __device__ __forceinline__ u32x4 pack8(f32x4 v0, f32x4 v1) { u32x4 w; w.x = cvt_pk_bf16(v0[0], v0[1]); w.y = cvt_pk_bf16(v0[2], v0[3]); w.z = cvt_pk_bf16(v1[0], v1[1]); w.w = cvt_pk_bf16(v1[2], v1[3]); return w; }
; #define GAS __attribute__((address_space(1)))
;     __device__ __forceinline__ void operator()(const f32x4 (&acc)[2][2][4][2], const Unit& u, int wr, int wc, int fr_in, int fq_in) const {
;     ...
;                     f32x4 p0, p1;
; #pragma unroll
;                     for (int i = 0; i < 4; ++i) { p0[i] = __shfl_xor(y[0][0][i], 16); p1[i] = __shfl_xor(y[0][1][i], 16); }
;                     if (fq == 0) { y[0][0] = y[0][0] * c0 - p0 * s0; y[0][1] = y[0][1] * c1 - p1 * s1; }
;                     else if (fq == 1) { y[0][0] = y[0][0] * c0 + p0 * s0; y[0][1] = y[0][1] * c1 + p1 * s1; }
;                     if (!isk) { bf16_t* qp = QN + (size_t)row * 1024 + (4 * (u.pn - 4) + wc) * 64 + 8 * fq;
;                         *(GAS u32x4*)(qp) = pack8(y[0][0], y[0][1]); *(GAS u32x4*)(qp + 32) = pack8(y[1][0], y[1][1]); }
;                     else { const int co = wc * 64 + 8 * fq; bf16_t* kp = KN + (size_t)row * 256 + co;
;                         *(GAS u32x4*)(kp) = pack8(y[0][0], y[0][1]); *(GAS u32x4*)(kp + 32) = pack8(y[1][0], y[1][1]);
;                         if (smp || t >= 1920) { float* d = out + (smp ? o_sk + ((size_t)(l * 16 + bb) * 128 + 64 + t) * 256 : o_pk + ((size_t)(l * 4 + bb) * 128 + (t - 1920)) * 256) + co;
;                             *(f32x4*)(d) = y[0][0]; *(f32x4*)(d + 4) = y[0][1]; *(f32x4*)(d + 32) = y[1][0]; *(f32x4*)(d + 36) = y[1][1]; } }
.LBB0_452:
	s_or_b64 exec, exec, s[38:39]
	v_pk_mul_f32 v[122:123], v[122:123], v[198:199]
	v_pk_mul_f32 v[120:121], v[120:121], v[196:197]
	v_pk_mul_f32 v[118:119], v[118:119], v[198:199]
	v_pk_mul_f32 v[116:117], v[116:117], v[196:197]
	s_waitcnt vmcnt(4)
	v_pk_mul_f32 v[122:123], v[130:131], v[122:123]
	v_pk_mul_f32 v[120:121], v[128:129], v[120:121]
	v_pk_mul_f32 v[116:117], v[124:125], v[116:117]
	v_pk_mul_f32 v[118:119], v[126:127], v[118:119]
	s_waitcnt lgkmcnt(6)
	v_cndmask_b32_e64 v148, 0, 1, s[56:57]
	v_ashrrev_i32_e32 v193, 31, v192
	s_mov_b64 s[58:59], -1
	v_cmp_ne_u32_e64 s[38:39], 1, v148
	s_andn2_b64 vcc, exec, s[56:57]
	s_waitcnt vmcnt(3)
	v_cvt_pk_bf16_f32 v152, v140, v141
	v_cvt_pk_bf16_f32 v153, v142, v143
	s_waitcnt vmcnt(1)
	v_cvt_pk_bf16_f32 v154, v144, v145
	v_cvt_pk_bf16_f32 v155, v146, v147
	v_cvt_pk_bf16_f32 v148, v120, v121
	s_waitcnt lgkmcnt(4)
	v_cvt_pk_bf16_f32 v149, v122, v123
	v_cvt_pk_bf16_f32 v150, v116, v117
	v_cvt_pk_bf16_f32 v151, v118, v119
	s_cbranch_vccnz .LBB0_454
	v_lshlrev_b64 v[156:157], 11, v[192:193]
	s_lshl_b32 s0, s95, 8
	v_lshl_add_u64 v[156:157], s[22:23], 0, v[156:157]
	s_add_i32 s78, s0, s93
	v_lshl_add_u64 v[156:157], s[78:79], 1, v[156:157]
	v_lshl_add_u64 v[156:157], v[194:195], 1, v[156:157]
	s_mov_b64 s[58:59], 0
	global_store_dwordx4 v[156:157], v[152:155], off sc1
	global_store_dwordx4 v[156:157], v[148:151], off offset:64 sc1
.LBB0_454:
	v_readlane_b32 s0, v255, 1
	s_andn2_b64 vcc, exec, s[58:59]
	s_nop 0
	v_add_u32_e32 v156, s0, v194
	v_ashrrev_i32_e32 v157, 31, v156
	s_cbranch_vccnz .LBB0_462
	v_lshlrev_b64 v[158:159], 9, v[192:193]
	s_movk_i32 s0, 0x77f
	v_lshl_add_u64 v[158:159], s[82:83], 0, v[158:159]
	v_cmp_lt_u32_e32 vcc, s0, v229
	v_lshl_add_u64 v[158:159], v[156:157], 1, v[158:159]
	s_or_b64 s[0:1], s[40:41], vcc
	global_store_dwordx4 v[158:159], v[152:155], off sc1
	global_store_dwordx4 v[158:159], v[148:151], off offset:64 sc1
	s_and_saveexec_b64 s[40:41], s[0:1]
	s_cbranch_execz .LBB0_461
	s_and_saveexec_b64 s[0:1], s[42:43]
	s_xor_b64 s[42:43], exec, s[0:1]
	v_ashrrev_i32_e32 v148, 11, v192
	v_add_u32_e32 v148, s75, v148
	v_ashrrev_i32_e32 v149, 31, v148
	v_lshlrev_b32_e32 v150, 8, v228
	v_mov_b32_e32 v151, v98
	v_lshlrev_b64 v[148:149], 15, v[148:149]
	v_lshl_add_u64 v[148:149], v[150:151], 0, v[148:149]
	s_mov_b64 s[0:1], 0x1188000
	v_lshl_add_u64 v[148:149], v[148:149], 0, s[0:1]
	s_andn2_saveexec_b64 s[42:43], s[42:43]
	v_add_u32_e32 v148, 0xffffe000, v192
	v_lshrrev_b32_e32 v148, 6, v148
	v_add_u32_e32 v148, s31, v148
	v_mov_b32_e32 v149, v98
	v_lshlrev_b64 v[148:149], 15, v[148:149]
	v_lshl_or_b32 v150, v227, 8, v217
	v_mov_b32_e32 v151, v98
	v_lshl_add_u64 v[148:149], v[148:149], 0, v[150:151]
	s_or_b64 exec, exec, s[42:43]
	v_lshl_add_u64 v[148:149], v[148:149], 2, s[64:65]
	v_lshl_add_u64 v[148:149], v[156:157], 2, v[148:149]
	global_store_dwordx4 v[148:149], v[140:143], off sc1
	global_store_dwordx4 v[148:149], v[144:147], off offset:16 sc1
	global_store_dwordx4 v[148:149], v[120:123], off offset:128 sc1
	global_store_dwordx4 v[148:149], v[116:119], off offset:144 sc1

; #define GAS __attribute__((address_space(1)))
; __device__ __forceinline__ u32x4 pack8(f32x4 v0, f32x4 v1) { u32x4 w; w.x = cvt_pk_bf16(v0[0], v0[1]); w.y = cvt_pk_bf16(v0[2], v0[3]); w.z = cvt_pk_bf16(v1[0], v1[1]); w.w = cvt_pk_bf16(v1[2], v1[3]); return w; }
; #define GAS __attribute__((address_space(1)))
;     __device__ __forceinline__ void operator()(const f32x4 (&acc)[2][2][4][2], const Unit& u, int wr, int wc, int fr_in, int fq_in) const {
;     ...
;                     f32x4 p0, p1;
; #pragma unroll
;                     for (int i = 0; i < 4; ++i) { p0[i] = __shfl_xor(y[0][0][i], 16); p1[i] = __shfl_xor(y[0][1][i], 16); }
;                     if (fq == 0) { y[0][0] = y[0][0] * c0 - p0 * s0; y[0][1] = y[0][1] * c1 - p1 * s1; }
;                     else if (fq == 1) { y[0][0] = y[0][0] * c0 + p0 * s0; y[0][1] = y[0][1] * c1 + p1 * s1; }
;                     if (!isk) { bf16_t* qp = QN + (size_t)row * 1024 + (4 * (u.pn - 4) + wc) * 64 + 8 * fq;
;                         *(GAS u32x4*)(qp) = pack8(y[0][0], y[0][1]); *(GAS u32x4*)(qp + 32) = pack8(y[1][0], y[1][1]); }
;                     else { const int co = wc * 64 + 8 * fq; bf16_t* kp = KN + (size_t)row * 256 + co;
;                         *(GAS u32x4*)(kp) = pack8(y[0][0], y[0][1]); *(GAS u32x4*)(kp + 32) = pack8(y[1][0], y[1][1]);
;                         if (smp || t >= 1920) { float* d = out + (smp ? o_sk + ((size_t)(l * 16 + bb) * 128 + 64 + t) * 256 : o_pk + ((size_t)(l * 4 + bb) * 128 + (t - 1920)) * 256) + co;
;                             *(f32x4*)(d) = y[0][0]; *(f32x4*)(d + 4) = y[0][1]; *(f32x4*)(d + 32) = y[1][0]; *(f32x4*)(d + 36) = y[1][1]; } }
.LBB0_470:
	s_or_b64 exec, exec, s[56:57]
	v_pk_mul_f32 v[106:107], v[106:107], v[158:159]
	v_pk_mul_f32 v[104:105], v[104:105], v[122:123]
	v_pk_mul_f32 v[102:103], v[102:103], v[158:159]
	v_pk_mul_f32 v[100:101], v[100:101], v[122:123]
	v_pk_mul_f32 v[106:107], v[130:131], v[106:107]
	v_pk_mul_f32 v[104:105], v[128:129], v[104:105]
	v_pk_mul_f32 v[102:103], v[126:127], v[102:103]
	v_pk_mul_f32 v[100:101], v[124:125], v[100:101]
	v_ashrrev_i32_e32 v155, 31, v154
	s_mov_b64 s[56:57], -1
	s_and_b64 vcc, exec, s[38:39]
	s_waitcnt vmcnt(3)
	v_cvt_pk_bf16_f32 v120, v112, v113
	v_cvt_pk_bf16_f32 v121, v114, v115
	v_cvt_pk_bf16_f32 v122, v108, v109
	v_cvt_pk_bf16_f32 v123, v110, v111
	s_waitcnt lgkmcnt(6)
	v_cvt_pk_bf16_f32 v116, v104, v105
	s_waitcnt lgkmcnt(4)
	v_cvt_pk_bf16_f32 v117, v106, v107
	v_cvt_pk_bf16_f32 v118, v100, v101
	v_cvt_pk_bf16_f32 v119, v102, v103
	s_cbranch_vccnz .LBB0_472
	s_waitcnt vmcnt(1)
	v_lshlrev_b64 v[140:141], 11, v[154:155]
	s_lshl_b32 s0, s95, 8
	v_lshl_add_u64 v[140:141], s[22:23], 0, v[140:141]
	s_add_i32 s78, s0, s93
	v_lshl_add_u64 v[140:141], s[78:79], 1, v[140:141]
	v_lshl_add_u64 v[140:141], v[194:195], 1, v[140:141]
	s_mov_b64 s[56:57], 0
	global_store_dwordx4 v[140:141], v[120:123], off sc1
	global_store_dwordx4 v[140:141], v[116:119], off offset:64 sc1
.LBB0_472:
	s_andn2_b64 vcc, exec, s[56:57]
	s_cbranch_vccnz .LBB0_480
	s_waitcnt vmcnt(1)
	v_lshlrev_b64 v[140:141], 9, v[154:155]
	s_movk_i32 s0, 0x77f
	v_lshl_add_u64 v[140:141], s[82:83], 0, v[140:141]
	v_cmp_lt_u32_e32 vcc, s0, v166
	v_lshl_add_u64 v[140:141], v[156:157], 1, v[140:141]
	s_or_b64 s[0:1], s[40:41], vcc
	global_store_dwordx4 v[140:141], v[120:123], off sc1
	global_store_dwordx4 v[140:141], v[116:119], off offset:64 sc1
	s_and_saveexec_b64 s[40:41], s[0:1]
	s_cbranch_execz .LBB0_479
	s_and_saveexec_b64 s[0:1], s[42:43]
	s_xor_b64 s[42:43], exec, s[0:1]
	v_ashrrev_i32_e32 v116, 11, v154
	v_add_u32_e32 v116, s75, v116
	v_ashrrev_i32_e32 v117, 31, v116
	v_lshlrev_b32_e32 v118, 8, v165
	v_mov_b32_e32 v119, v98
	v_lshlrev_b64 v[116:117], 15, v[116:117]
	v_lshl_add_u64 v[116:117], v[118:119], 0, v[116:117]
	s_mov_b64 s[0:1], 0x1188000
	v_lshl_add_u64 v[116:117], v[116:117], 0, s[0:1]
	s_andn2_saveexec_b64 s[42:43], s[42:43]
	v_add_u32_e32 v116, 0xffffe010, v192
	v_lshrrev_b32_e32 v116, 6, v116
	v_add_u32_e32 v116, s31, v116
	v_mov_b32_e32 v117, v98
	v_lshlrev_b64 v[116:117], 15, v[116:117]
	v_lshl_or_b32 v118, v164, 8, v217
	v_mov_b32_e32 v119, v98
	v_lshl_add_u64 v[116:117], v[116:117], 0, v[118:119]
	s_or_b64 exec, exec, s[42:43]
	v_lshl_add_u64 v[116:117], v[116:117], 2, s[64:65]
	v_lshl_add_u64 v[116:117], v[156:157], 2, v[116:117]
	global_store_dwordx4 v[116:117], v[112:115], off sc1
	global_store_dwordx4 v[116:117], v[108:111], off offset:16 sc1
	global_store_dwordx4 v[116:117], v[104:107], off offset:128 sc1
	global_store_dwordx4 v[116:117], v[100:103], off offset:144 sc1

; #define GAS __attribute__((address_space(1)))
; __device__ __forceinline__ u32x4 pack8(f32x4 v0, f32x4 v1) { u32x4 w; w.x = cvt_pk_bf16(v0[0], v0[1]); w.y = cvt_pk_bf16(v0[2], v0[3]); w.z = cvt_pk_bf16(v1[0], v1[1]); w.w = cvt_pk_bf16(v1[2], v1[3]); return w; }
; #define GAS __attribute__((address_space(1)))
;     __device__ __forceinline__ void operator()(const f32x4 (&acc)[2][2][4][2], const Unit& u, int wr, int wc, int fr_in, int fq_in) const {
;     ...
;                     f32x4 p0, p1;
; #pragma unroll
;                     for (int i = 0; i < 4; ++i) { p0[i] = __shfl_xor(y[0][0][i], 16); p1[i] = __shfl_xor(y[0][1][i], 16); }
;                     if (fq == 0) { y[0][0] = y[0][0] * c0 - p0 * s0; y[0][1] = y[0][1] * c1 - p1 * s1; }
;                     else if (fq == 1) { y[0][0] = y[0][0] * c0 + p0 * s0; y[0][1] = y[0][1] * c1 + p1 * s1; }
;                     if (!isk) { bf16_t* qp = QN + (size_t)row * 1024 + (4 * (u.pn - 4) + wc) * 64 + 8 * fq;
;                         *(GAS u32x4*)(qp) = pack8(y[0][0], y[0][1]); *(GAS u32x4*)(qp + 32) = pack8(y[1][0], y[1][1]); }
;                     else { const int co = wc * 64 + 8 * fq; bf16_t* kp = KN + (size_t)row * 256 + co;
;                         *(GAS u32x4*)(kp) = pack8(y[0][0], y[0][1]); *(GAS u32x4*)(kp + 32) = pack8(y[1][0], y[1][1]);
;                         if (smp || t >= 1920) { float* d = out + (smp ? o_sk + ((size_t)(l * 16 + bb) * 128 + 64 + t) * 256 : o_pk + ((size_t)(l * 4 + bb) * 128 + (t - 1920)) * 256) + co;
;                             *(f32x4*)(d) = y[0][0]; *(f32x4*)(d + 4) = y[0][1]; *(f32x4*)(d + 32) = y[1][0]; *(f32x4*)(d + 36) = y[1][1]; } }
.LBB0_488:
	s_or_b64 exec, exec, s[56:57]
	v_pk_mul_f32 v[88:89], v[88:89], v[140:141]
	v_pk_mul_f32 v[86:87], v[86:87], v[122:123]
	v_pk_mul_f32 v[84:85], v[84:85], v[140:141]
	v_pk_mul_f32 v[82:83], v[82:83], v[122:123]
	v_pk_mul_f32 v[88:89], v[130:131], v[88:89]
	v_pk_mul_f32 v[86:87], v[128:129], v[86:87]
	v_pk_mul_f32 v[84:85], v[126:127], v[84:85]
	v_pk_mul_f32 v[82:83], v[124:125], v[82:83]
	v_ashrrev_i32_e32 v121, 31, v120
	s_mov_b64 s[56:57], -1
	s_and_b64 vcc, exec, s[38:39]
	s_waitcnt vmcnt(3)
	v_cvt_pk_bf16_f32 v104, v94, v95
	v_cvt_pk_bf16_f32 v105, v96, v97
	s_waitcnt vmcnt(1)
	v_cvt_pk_bf16_f32 v106, v90, v91
	v_cvt_pk_bf16_f32 v107, v92, v93
	s_waitcnt lgkmcnt(6)
	v_cvt_pk_bf16_f32 v100, v86, v87
	s_waitcnt lgkmcnt(4)
	v_cvt_pk_bf16_f32 v101, v88, v89
	v_cvt_pk_bf16_f32 v102, v82, v83
	v_cvt_pk_bf16_f32 v103, v84, v85
	s_cbranch_vccnz .LBB0_490
	v_lshlrev_b64 v[108:109], 11, v[120:121]
	s_lshl_b32 s0, s95, 8
	v_lshl_add_u64 v[108:109], s[22:23], 0, v[108:109]
	s_add_i32 s78, s0, s93
	v_lshl_add_u64 v[108:109], s[78:79], 1, v[108:109]
	v_lshl_add_u64 v[108:109], v[194:195], 1, v[108:109]
	s_mov_b64 s[56:57], 0
	global_store_dwordx4 v[108:109], v[104:107], off sc1
	global_store_dwordx4 v[108:109], v[100:103], off offset:64 sc1
.LBB0_490:
	s_andn2_b64 vcc, exec, s[56:57]
	s_cbranch_vccnz .LBB0_498
	v_lshlrev_b64 v[108:109], 9, v[120:121]
	s_movk_i32 s0, 0x77f
	v_lshl_add_u64 v[108:109], s[82:83], 0, v[108:109]
	v_cmp_lt_u32_e32 vcc, s0, v148
	v_lshl_add_u64 v[108:109], v[156:157], 1, v[108:109]
	s_or_b64 s[0:1], s[40:41], vcc
	global_store_dwordx4 v[108:109], v[104:107], off sc1
	global_store_dwordx4 v[108:109], v[100:103], off offset:64 sc1
	s_and_saveexec_b64 s[40:41], s[0:1]
	s_cbranch_execz .LBB0_497
	s_and_saveexec_b64 s[0:1], s[42:43]
	s_xor_b64 s[42:43], exec, s[0:1]
	v_ashrrev_i32_e32 v100, 11, v120
	v_add_u32_e32 v100, s75, v100
	v_ashrrev_i32_e32 v101, 31, v100
	v_lshlrev_b32_e32 v102, 8, v147
	v_mov_b32_e32 v103, v98
	v_lshlrev_b64 v[100:101], 15, v[100:101]
	v_lshl_add_u64 v[100:101], v[102:103], 0, v[100:101]
	s_mov_b64 s[0:1], 0x1188000
	v_lshl_add_u64 v[100:101], v[100:101], 0, s[0:1]
	s_andn2_saveexec_b64 s[42:43], s[42:43]
	v_add_u32_e32 v100, 0xffffe020, v192
	v_lshrrev_b32_e32 v100, 6, v100
	v_add_u32_e32 v100, s31, v100
	v_mov_b32_e32 v101, v98
	v_lshlrev_b64 v[100:101], 15, v[100:101]
	v_lshl_or_b32 v102, v146, 8, v217
	v_mov_b32_e32 v103, v98
	v_lshl_add_u64 v[100:101], v[100:101], 0, v[102:103]
	s_or_b64 exec, exec, s[42:43]
	v_lshl_add_u64 v[100:101], v[100:101], 2, s[64:65]
	v_lshl_add_u64 v[100:101], v[156:157], 2, v[100:101]
	global_store_dwordx4 v[100:101], v[94:97], off sc1
	global_store_dwordx4 v[100:101], v[90:93], off offset:16 sc1
	global_store_dwordx4 v[100:101], v[86:89], off offset:128 sc1
	global_store_dwordx4 v[100:101], v[82:85], off offset:144 sc1

; #define GAS __attribute__((address_space(1)))
; __device__ __forceinline__ u32x4 pack8(f32x4 v0, f32x4 v1) { u32x4 w; w.x = cvt_pk_bf16(v0[0], v0[1]); w.y = cvt_pk_bf16(v0[2], v0[3]); w.z = cvt_pk_bf16(v1[0], v1[1]); w.w = cvt_pk_bf16(v1[2], v1[3]); return w; }
; #define GAS __attribute__((address_space(1)))
;     __device__ __forceinline__ void operator()(const f32x4 (&acc)[2][2][4][2], const Unit& u, int wr, int wc, int fr_in, int fq_in) const {
;     ...
;                     f32x4 p0, p1;
; #pragma unroll
;                     for (int i = 0; i < 4; ++i) { p0[i] = __shfl_xor(y[0][0][i], 16); p1[i] = __shfl_xor(y[0][1][i], 16); }
;                     if (fq == 0) { y[0][0] = y[0][0] * c0 - p0 * s0; y[0][1] = y[0][1] * c1 - p1 * s1; }
;                     else if (fq == 1) { y[0][0] = y[0][0] * c0 + p0 * s0; y[0][1] = y[0][1] * c1 + p1 * s1; }
;                     if (!isk) { bf16_t* qp = QN + (size_t)row * 1024 + (4 * (u.pn - 4) + wc) * 64 + 8 * fq;
;                         *(GAS u32x4*)(qp) = pack8(y[0][0], y[0][1]); *(GAS u32x4*)(qp + 32) = pack8(y[1][0], y[1][1]); }
;                     else { const int co = wc * 64 + 8 * fq; bf16_t* kp = KN + (size_t)row * 256 + co;
;                         *(GAS u32x4*)(kp) = pack8(y[0][0], y[0][1]); *(GAS u32x4*)(kp + 32) = pack8(y[1][0], y[1][1]);
;                         if (smp || t >= 1920) { float* d = out + (smp ? o_sk + ((size_t)(l * 16 + bb) * 128 + 64 + t) * 256 : o_pk + ((size_t)(l * 4 + bb) * 128 + (t - 1920)) * 256) + co;
;                             *(f32x4*)(d) = y[0][0]; *(f32x4*)(d + 4) = y[0][1]; *(f32x4*)(d + 32) = y[1][0]; *(f32x4*)(d + 36) = y[1][1]; } }
.LBB0_506:
	s_or_b64 exec, exec, s[56:57]
	v_pk_mul_f32 v[72:73], v[72:73], v[108:109]
	v_pk_mul_f32 v[70:71], v[70:71], v[106:107]
	v_pk_mul_f32 v[68:69], v[68:69], v[108:109]
	v_pk_mul_f32 v[66:67], v[66:67], v[106:107]
	v_pk_mul_f32 v[72:73], v[130:131], v[72:73]
	v_pk_mul_f32 v[70:71], v[128:129], v[70:71]
	v_pk_mul_f32 v[68:69], v[126:127], v[68:69]
	v_pk_mul_f32 v[66:67], v[124:125], v[66:67]
	v_ashrrev_i32_e32 v105, 31, v104
	s_mov_b64 s[56:57], -1
	s_and_b64 vcc, exec, s[38:39]
	s_waitcnt vmcnt(3)
	v_cvt_pk_bf16_f32 v86, v78, v79
	v_cvt_pk_bf16_f32 v87, v80, v81
	s_waitcnt vmcnt(1)
	v_cvt_pk_bf16_f32 v88, v74, v75
	v_cvt_pk_bf16_f32 v89, v76, v77
	s_waitcnt lgkmcnt(6)
	v_cvt_pk_bf16_f32 v82, v70, v71
	s_waitcnt lgkmcnt(4)
	v_cvt_pk_bf16_f32 v83, v72, v73
	v_cvt_pk_bf16_f32 v84, v66, v67
	v_cvt_pk_bf16_f32 v85, v68, v69
	s_cbranch_vccnz .LBB0_508
	v_lshlrev_b64 v[90:91], 11, v[104:105]
	s_lshl_b32 s0, s95, 8
	v_lshl_add_u64 v[90:91], s[22:23], 0, v[90:91]
	s_add_i32 s78, s0, s93
	v_lshl_add_u64 v[90:91], s[78:79], 1, v[90:91]
	v_lshl_add_u64 v[90:91], v[194:195], 1, v[90:91]
	s_mov_b64 s[56:57], 0
	global_store_dwordx4 v[90:91], v[86:89], off sc1
	global_store_dwordx4 v[90:91], v[82:85], off offset:64 sc1
.LBB0_508:
	s_andn2_b64 vcc, exec, s[56:57]
	s_cbranch_vccnz .LBB0_516
	v_lshlrev_b64 v[90:91], 9, v[104:105]
	s_movk_i32 s0, 0x77f
	v_lshl_add_u64 v[90:91], s[82:83], 0, v[90:91]
	v_cmp_lt_u32_e32 vcc, s0, v116
	v_lshl_add_u64 v[90:91], v[156:157], 1, v[90:91]
	s_or_b64 s[0:1], s[40:41], vcc
	global_store_dwordx4 v[90:91], v[86:89], off sc1
	global_store_dwordx4 v[90:91], v[82:85], off offset:64 sc1
	s_and_saveexec_b64 s[40:41], s[0:1]
	s_cbranch_execz .LBB0_515
	s_and_saveexec_b64 s[0:1], s[42:43]
	s_xor_b64 s[42:43], exec, s[0:1]
	v_ashrrev_i32_e32 v82, 11, v104
	v_add_u32_e32 v82, s75, v82
	v_ashrrev_i32_e32 v83, 31, v82
	v_lshlrev_b32_e32 v84, 8, v115
	v_mov_b32_e32 v85, v98
	v_lshlrev_b64 v[82:83], 15, v[82:83]
	v_lshl_add_u64 v[82:83], v[84:85], 0, v[82:83]
	s_mov_b64 s[0:1], 0x1188000
	v_lshl_add_u64 v[82:83], v[82:83], 0, s[0:1]
	s_andn2_saveexec_b64 s[42:43], s[42:43]
	v_add_u32_e32 v82, 0xffffe030, v192
	v_lshrrev_b32_e32 v82, 6, v82
	v_add_u32_e32 v82, s31, v82
	v_mov_b32_e32 v83, v98
	v_lshlrev_b64 v[82:83], 15, v[82:83]
	v_lshl_or_b32 v84, v114, 8, v217
	v_mov_b32_e32 v85, v98
	v_lshl_add_u64 v[82:83], v[82:83], 0, v[84:85]
	s_or_b64 exec, exec, s[42:43]
	v_lshl_add_u64 v[82:83], v[82:83], 2, s[64:65]
	v_lshl_add_u64 v[82:83], v[156:157], 2, v[82:83]
	global_store_dwordx4 v[82:83], v[78:81], off sc1
	global_store_dwordx4 v[82:83], v[74:77], off offset:16 sc1
	global_store_dwordx4 v[82:83], v[70:73], off offset:128 sc1
	global_store_dwordx4 v[82:83], v[66:69], off offset:144 sc1

; #define GAS __attribute__((address_space(1)))
; __device__ __forceinline__ u32x4 pack8(f32x4 v0, f32x4 v1) { u32x4 w; w.x = cvt_pk_bf16(v0[0], v0[1]); w.y = cvt_pk_bf16(v0[2], v0[3]); w.z = cvt_pk_bf16(v1[0], v1[1]); w.w = cvt_pk_bf16(v1[2], v1[3]); return w; }
; #define GAS __attribute__((address_space(1)))
;     __device__ __forceinline__ void operator()(const f32x4 (&acc)[2][2][4][2], const Unit& u, int wr, int wc, int fr_in, int fq_in) const {
;     ...
;                     f32x4 p0, p1;
; #pragma unroll
;                     for (int i = 0; i < 4; ++i) { p0[i] = __shfl_xor(y[0][0][i], 16); p1[i] = __shfl_xor(y[0][1][i], 16); }
;                     if (fq == 0) { y[0][0] = y[0][0] * c0 - p0 * s0; y[0][1] = y[0][1] * c1 - p1 * s1; }
;                     else if (fq == 1) { y[0][0] = y[0][0] * c0 + p0 * s0; y[0][1] = y[0][1] * c1 + p1 * s1; }
;                     if (!isk) { bf16_t* qp = QN + (size_t)row * 1024 + (4 * (u.pn - 4) + wc) * 64 + 8 * fq;
;                         *(GAS u32x4*)(qp) = pack8(y[0][0], y[0][1]); *(GAS u32x4*)(qp + 32) = pack8(y[1][0], y[1][1]); }
;                     else { const int co = wc * 64 + 8 * fq; bf16_t* kp = KN + (size_t)row * 256 + co;
;                         *(GAS u32x4*)(kp) = pack8(y[0][0], y[0][1]); *(GAS u32x4*)(kp + 32) = pack8(y[1][0], y[1][1]);
;                         if (smp || t >= 1920) { float* d = out + (smp ? o_sk + ((size_t)(l * 16 + bb) * 128 + 64 + t) * 256 : o_pk + ((size_t)(l * 4 + bb) * 128 + (t - 1920)) * 256) + co;
;                             *(f32x4*)(d) = y[0][0]; *(f32x4*)(d + 4) = y[0][1]; *(f32x4*)(d + 32) = y[1][0]; *(f32x4*)(d + 36) = y[1][1]; } }
.LBB0_524:
	s_or_b64 exec, exec, s[56:57]
	v_pk_mul_f32 v[56:57], v[56:57], v[90:91]
	v_pk_mul_f32 v[54:55], v[54:55], v[88:89]
	v_pk_mul_f32 v[52:53], v[52:53], v[90:91]
	v_pk_mul_f32 v[50:51], v[50:51], v[88:89]
	v_pk_mul_f32 v[56:57], v[130:131], v[56:57]
	v_pk_mul_f32 v[54:55], v[128:129], v[54:55]
	v_pk_mul_f32 v[52:53], v[126:127], v[52:53]
	v_pk_mul_f32 v[50:51], v[124:125], v[50:51]
	v_ashrrev_i32_e32 v87, 31, v86
	s_mov_b64 s[56:57], -1
	s_and_b64 vcc, exec, s[38:39]
	s_waitcnt vmcnt(3)
	v_cvt_pk_bf16_f32 v70, v62, v63
	v_cvt_pk_bf16_f32 v71, v64, v65
	s_waitcnt vmcnt(1)
	v_cvt_pk_bf16_f32 v72, v58, v59
	v_cvt_pk_bf16_f32 v73, v60, v61
	s_waitcnt lgkmcnt(6)
	v_cvt_pk_bf16_f32 v66, v54, v55
	s_waitcnt lgkmcnt(4)
	v_cvt_pk_bf16_f32 v67, v56, v57
	v_cvt_pk_bf16_f32 v68, v50, v51
	v_cvt_pk_bf16_f32 v69, v52, v53
	s_cbranch_vccnz .LBB0_526
	v_lshlrev_b64 v[74:75], 11, v[86:87]
	s_lshl_b32 s0, s95, 8
	v_lshl_add_u64 v[74:75], s[22:23], 0, v[74:75]
	s_add_i32 s78, s0, s93
	v_lshl_add_u64 v[74:75], s[78:79], 1, v[74:75]
	v_lshl_add_u64 v[74:75], v[194:195], 1, v[74:75]
	s_mov_b64 s[56:57], 0
	global_store_dwordx4 v[74:75], v[70:73], off sc1
	global_store_dwordx4 v[74:75], v[66:69], off offset:64 sc1
.LBB0_526:
	s_andn2_b64 vcc, exec, s[56:57]
	s_cbranch_vccnz .LBB0_534
	v_lshlrev_b64 v[74:75], 9, v[86:87]
	s_movk_i32 s0, 0x77f
	v_lshl_add_u64 v[74:75], s[82:83], 0, v[74:75]
	v_cmp_lt_u32_e32 vcc, s0, v97
	v_lshl_add_u64 v[74:75], v[156:157], 1, v[74:75]
	s_or_b64 s[0:1], s[40:41], vcc
	global_store_dwordx4 v[74:75], v[70:73], off sc1
	global_store_dwordx4 v[74:75], v[66:69], off offset:64 sc1
	s_and_saveexec_b64 s[40:41], s[0:1]
	s_cbranch_execz .LBB0_533
	s_and_saveexec_b64 s[0:1], s[42:43]
	s_xor_b64 s[42:43], exec, s[0:1]
	v_ashrrev_i32_e32 v66, 11, v86
	v_add_u32_e32 v66, s75, v66
	v_ashrrev_i32_e32 v67, 31, v66
	v_lshlrev_b32_e32 v68, 8, v96
	v_mov_b32_e32 v69, v98
	v_lshlrev_b64 v[66:67], 15, v[66:67]
	v_lshl_add_u64 v[66:67], v[68:69], 0, v[66:67]
	s_mov_b64 s[0:1], 0x1188000
	v_lshl_add_u64 v[66:67], v[66:67], 0, s[0:1]
	s_andn2_saveexec_b64 s[42:43], s[42:43]
	v_add_u32_e32 v66, 0xffffe080, v192
	v_lshrrev_b32_e32 v66, 6, v66
	v_add_u32_e32 v66, s31, v66
	v_mov_b32_e32 v67, v98
	v_lshlrev_b64 v[66:67], 15, v[66:67]
	v_lshl_or_b32 v68, v227, 8, v217
	v_mov_b32_e32 v69, v98
	v_lshl_add_u64 v[66:67], v[66:67], 0, v[68:69]
	s_or_b64 exec, exec, s[42:43]
	v_lshl_add_u64 v[66:67], v[66:67], 2, s[64:65]
	v_lshl_add_u64 v[66:67], v[156:157], 2, v[66:67]
	global_store_dwordx4 v[66:67], v[62:65], off sc1
	global_store_dwordx4 v[66:67], v[58:61], off offset:16 sc1
	global_store_dwordx4 v[66:67], v[54:57], off offset:128 sc1
	global_store_dwordx4 v[66:67], v[50:53], off offset:144 sc1

; #define GAS __attribute__((address_space(1)))
; __device__ __forceinline__ u32x4 pack8(f32x4 v0, f32x4 v1) { u32x4 w; w.x = cvt_pk_bf16(v0[0], v0[1]); w.y = cvt_pk_bf16(v0[2], v0[3]); w.z = cvt_pk_bf16(v1[0], v1[1]); w.w = cvt_pk_bf16(v1[2], v1[3]); return w; }
; #define GAS __attribute__((address_space(1)))
;     __device__ __forceinline__ void operator()(const f32x4 (&acc)[2][2][4][2], const Unit& u, int wr, int wc, int fr_in, int fq_in) const {
;     ...
;                         for (int n = 0; n < 2; ++n) y[bj][n] = y[bj][n] * rstd * gv[bj][n];
;                     f32x4 p0, p1;
; #pragma unroll
;                     for (int i = 0; i < 4; ++i) { p0[i] = __shfl_xor(y[0][0][i], 16); p1[i] = __shfl_xor(y[0][1][i], 16); }
;                     if (fq == 0) { y[0][0] = y[0][0] * c0 - p0 * s0; y[0][1] = y[0][1] * c1 - p1 * s1; }
;                     else if (fq == 1) { y[0][0] = y[0][0] * c0 + p0 * s0; y[0][1] = y[0][1] * c1 + p1 * s1; }
;                     if (!isk) { bf16_t* qp = QN + (size_t)row * 1024 + (4 * (u.pn - 4) + wc) * 64 + 8 * fq;
;                         *(GAS u32x4*)(qp) = pack8(y[0][0], y[0][1]); *(GAS u32x4*)(qp + 32) = pack8(y[1][0], y[1][1]); }
;                     else { const int co = wc * 64 + 8 * fq; bf16_t* kp = KN + (size_t)row * 256 + co;
;                         *(GAS u32x4*)(kp) = pack8(y[0][0], y[0][1]); *(GAS u32x4*)(kp + 32) = pack8(y[1][0], y[1][1]);
;                         if (smp || t >= 1920) { float* d = out + (smp ? o_sk + ((size_t)(l * 16 + bb) * 128 + 64 + t) * 256 : o_pk + ((size_t)(l * 4 + bb) * 128 + (t - 1920)) * 256) + co;
;                             *(f32x4*)(d) = y[0][0]; *(f32x4*)(d + 4) = y[0][1]; *(f32x4*)(d + 32) = y[1][0]; *(f32x4*)(d + 36) = y[1][1]; } }
.LBB0_542:
	s_or_b64 exec, exec, s[56:57]
	v_pk_mul_f32 v[40:41], v[40:41], v[74:75]
	v_pk_mul_f32 v[38:39], v[38:39], v[72:73]
	v_pk_mul_f32 v[36:37], v[36:37], v[74:75]
	v_pk_mul_f32 v[34:35], v[34:35], v[72:73]
	v_pk_mul_f32 v[40:41], v[130:131], v[40:41]
	v_pk_mul_f32 v[38:39], v[128:129], v[38:39]
	v_pk_mul_f32 v[36:37], v[126:127], v[36:37]
	v_pk_mul_f32 v[34:35], v[124:125], v[34:35]
	v_ashrrev_i32_e32 v71, 31, v70
	s_mov_b64 s[56:57], -1
	s_and_b64 vcc, exec, s[38:39]
	s_waitcnt vmcnt(3)
	v_cvt_pk_bf16_f32 v54, v46, v47
	v_cvt_pk_bf16_f32 v55, v48, v49
	s_waitcnt vmcnt(1)
	v_cvt_pk_bf16_f32 v56, v42, v43
	v_cvt_pk_bf16_f32 v57, v44, v45
	s_waitcnt lgkmcnt(6)
	v_cvt_pk_bf16_f32 v50, v38, v39
	s_waitcnt lgkmcnt(4)
	v_cvt_pk_bf16_f32 v51, v40, v41
	v_cvt_pk_bf16_f32 v52, v34, v35
	v_cvt_pk_bf16_f32 v53, v36, v37
	s_cbranch_vccnz .LBB0_544
	v_lshlrev_b64 v[58:59], 11, v[70:71]
	s_lshl_b32 s0, s95, 8
	v_lshl_add_u64 v[58:59], s[22:23], 0, v[58:59]
	s_add_i32 s78, s0, s93
	v_lshl_add_u64 v[58:59], s[78:79], 1, v[58:59]
	v_lshl_add_u64 v[58:59], v[194:195], 1, v[58:59]
	s_mov_b64 s[56:57], 0
	global_store_dwordx4 v[58:59], v[54:57], off sc1
	global_store_dwordx4 v[58:59], v[50:53], off offset:64 sc1
.LBB0_544:
	s_andn2_b64 vcc, exec, s[56:57]
	s_cbranch_vccnz .LBB0_552
	v_lshlrev_b64 v[58:59], 9, v[70:71]
	s_movk_i32 s0, 0x77f
	v_lshl_add_u64 v[58:59], s[82:83], 0, v[58:59]
	v_cmp_lt_u32_e32 vcc, s0, v81
	v_lshl_add_u64 v[58:59], v[156:157], 1, v[58:59]
	s_or_b64 s[0:1], s[40:41], vcc
	global_store_dwordx4 v[58:59], v[54:57], off sc1
	global_store_dwordx4 v[58:59], v[50:53], off offset:64 sc1
	s_and_saveexec_b64 s[40:41], s[0:1]
	s_cbranch_execz .LBB0_551
	s_and_saveexec_b64 s[0:1], s[42:43]
	s_xor_b64 s[42:43], exec, s[0:1]
	v_ashrrev_i32_e32 v50, 11, v70
	v_add_u32_e32 v50, s75, v50
	v_ashrrev_i32_e32 v51, 31, v50
	v_lshlrev_b32_e32 v52, 8, v80
	v_mov_b32_e32 v53, v98
	v_lshlrev_b64 v[50:51], 15, v[50:51]
	v_lshl_add_u64 v[50:51], v[52:53], 0, v[50:51]
	s_mov_b64 s[0:1], 0x1188000
	v_lshl_add_u64 v[50:51], v[50:51], 0, s[0:1]
	s_andn2_saveexec_b64 s[42:43], s[42:43]
	v_add_u32_e32 v50, 0xffffe090, v192
	v_lshrrev_b32_e32 v50, 6, v50
	v_add_u32_e32 v50, s31, v50
	v_mov_b32_e32 v51, v98
	v_lshlrev_b64 v[50:51], 15, v[50:51]
	v_lshl_or_b32 v52, v164, 8, v217
	v_mov_b32_e32 v53, v98
	v_lshl_add_u64 v[50:51], v[50:51], 0, v[52:53]
	s_or_b64 exec, exec, s[42:43]
	v_lshl_add_u64 v[50:51], v[50:51], 2, s[64:65]
	v_lshl_add_u64 v[50:51], v[156:157], 2, v[50:51]
	global_store_dwordx4 v[50:51], v[46:49], off sc1
	global_store_dwordx4 v[50:51], v[42:45], off offset:16 sc1
	global_store_dwordx4 v[50:51], v[38:41], off offset:128 sc1
	global_store_dwordx4 v[50:51], v[34:37], off offset:144 sc1

; #define GAS __attribute__((address_space(1)))
; __device__ __forceinline__ u32x4 pack8(f32x4 v0, f32x4 v1) { u32x4 w; w.x = cvt_pk_bf16(v0[0], v0[1]); w.y = cvt_pk_bf16(v0[2], v0[3]); w.z = cvt_pk_bf16(v1[0], v1[1]); w.w = cvt_pk_bf16(v1[2], v1[3]); return w; }
; #define GAS __attribute__((address_space(1)))
;     __device__ __forceinline__ void operator()(const f32x4 (&acc)[2][2][4][2], const Unit& u, int wr, int wc, int fr_in, int fq_in) const {
;     ...
;                         for (int n = 0; n < 2; ++n) y[bj][n] = y[bj][n] * rstd * gv[bj][n];
;                     f32x4 p0, p1;
; #pragma unroll
;                     for (int i = 0; i < 4; ++i) { p0[i] = __shfl_xor(y[0][0][i], 16); p1[i] = __shfl_xor(y[0][1][i], 16); }
;                     if (fq == 0) { y[0][0] = y[0][0] * c0 - p0 * s0; y[0][1] = y[0][1] * c1 - p1 * s1; }
;                     else if (fq == 1) { y[0][0] = y[0][0] * c0 + p0 * s0; y[0][1] = y[0][1] * c1 + p1 * s1; }
;                     if (!isk) { bf16_t* qp = QN + (size_t)row * 1024 + (4 * (u.pn - 4) + wc) * 64 + 8 * fq;
;                         *(GAS u32x4*)(qp) = pack8(y[0][0], y[0][1]); *(GAS u32x4*)(qp + 32) = pack8(y[1][0], y[1][1]); }
;                     else { const int co = wc * 64 + 8 * fq; bf16_t* kp = KN + (size_t)row * 256 + co;
;                         *(GAS u32x4*)(kp) = pack8(y[0][0], y[0][1]); *(GAS u32x4*)(kp + 32) = pack8(y[1][0], y[1][1]);
;                         if (smp || t >= 1920) { float* d = out + (smp ? o_sk + ((size_t)(l * 16 + bb) * 128 + 64 + t) * 256 : o_pk + ((size_t)(l * 4 + bb) * 128 + (t - 1920)) * 256) + co;
;                             *(f32x4*)(d) = y[0][0]; *(f32x4*)(d + 4) = y[0][1]; *(f32x4*)(d + 32) = y[1][0]; *(f32x4*)(d + 36) = y[1][1]; } }
.LBB0_560:
	s_or_b64 exec, exec, s[56:57]
	v_pk_mul_f32 v[24:25], v[24:25], v[58:59]
	v_pk_mul_f32 v[22:23], v[22:23], v[56:57]
	v_pk_mul_f32 v[20:21], v[20:21], v[58:59]
	v_pk_mul_f32 v[18:19], v[18:19], v[56:57]
	v_pk_mul_f32 v[24:25], v[130:131], v[24:25]
	v_pk_mul_f32 v[22:23], v[128:129], v[22:23]
	v_pk_mul_f32 v[20:21], v[126:127], v[20:21]
	v_pk_mul_f32 v[18:19], v[124:125], v[18:19]
	v_ashrrev_i32_e32 v55, 31, v54
	s_mov_b64 s[56:57], -1
	s_and_b64 vcc, exec, s[38:39]
	s_waitcnt vmcnt(3)
	v_cvt_pk_bf16_f32 v38, v30, v31
	v_cvt_pk_bf16_f32 v39, v32, v33
	s_waitcnt vmcnt(1)
	v_cvt_pk_bf16_f32 v40, v26, v27
	v_cvt_pk_bf16_f32 v41, v28, v29
	s_waitcnt lgkmcnt(6)
	v_cvt_pk_bf16_f32 v34, v22, v23
	s_waitcnt lgkmcnt(4)
	v_cvt_pk_bf16_f32 v35, v24, v25
	v_cvt_pk_bf16_f32 v36, v18, v19
	v_cvt_pk_bf16_f32 v37, v20, v21
	s_cbranch_vccnz .LBB0_562
	v_lshlrev_b64 v[42:43], 11, v[54:55]
	s_lshl_b32 s0, s95, 8
	v_lshl_add_u64 v[42:43], s[22:23], 0, v[42:43]
	s_add_i32 s78, s0, s93
	v_lshl_add_u64 v[42:43], s[78:79], 1, v[42:43]
	v_lshl_add_u64 v[42:43], v[194:195], 1, v[42:43]
	s_mov_b64 s[56:57], 0
	global_store_dwordx4 v[42:43], v[38:41], off sc1
	global_store_dwordx4 v[42:43], v[34:37], off offset:64 sc1
.LBB0_562:
	s_andn2_b64 vcc, exec, s[56:57]
	s_cbranch_vccnz .LBB0_570
	v_lshlrev_b64 v[42:43], 9, v[54:55]
	s_movk_i32 s0, 0x77f
	v_lshl_add_u64 v[42:43], s[82:83], 0, v[42:43]
	v_cmp_lt_u32_e32 vcc, s0, v65
	v_lshl_add_u64 v[42:43], v[156:157], 1, v[42:43]
	s_or_b64 s[0:1], s[40:41], vcc
	global_store_dwordx4 v[42:43], v[38:41], off sc1
	global_store_dwordx4 v[42:43], v[34:37], off offset:64 sc1
	s_and_saveexec_b64 s[40:41], s[0:1]
	s_cbranch_execz .LBB0_569
	s_and_saveexec_b64 s[0:1], s[42:43]
	s_xor_b64 s[42:43], exec, s[0:1]
	v_ashrrev_i32_e32 v34, 11, v54
	v_add_u32_e32 v34, s75, v34
	v_ashrrev_i32_e32 v35, 31, v34
	v_lshlrev_b32_e32 v36, 8, v64
	v_mov_b32_e32 v37, v98
	v_lshlrev_b64 v[34:35], 15, v[34:35]
	v_lshl_add_u64 v[34:35], v[36:37], 0, v[34:35]
	s_mov_b64 s[0:1], 0x1188000
	v_lshl_add_u64 v[34:35], v[34:35], 0, s[0:1]
	s_andn2_saveexec_b64 s[42:43], s[42:43]
	v_add_u32_e32 v34, 0xffffe0a0, v192
	v_lshrrev_b32_e32 v34, 6, v34
	v_add_u32_e32 v34, s31, v34
	v_mov_b32_e32 v35, v98
	v_lshlrev_b64 v[34:35], 15, v[34:35]
	v_lshl_or_b32 v36, v146, 8, v217
	v_mov_b32_e32 v37, v98
	v_lshl_add_u64 v[34:35], v[34:35], 0, v[36:37]
	s_or_b64 exec, exec, s[42:43]
	v_lshl_add_u64 v[34:35], v[34:35], 2, s[64:65]
	v_lshl_add_u64 v[34:35], v[156:157], 2, v[34:35]
	global_store_dwordx4 v[34:35], v[30:33], off sc1
	global_store_dwordx4 v[34:35], v[26:29], off offset:16 sc1
	global_store_dwordx4 v[34:35], v[22:25], off offset:128 sc1
	global_store_dwordx4 v[34:35], v[18:21], off offset:144 sc1

; #define GAS __attribute__((address_space(1)))
; __device__ __forceinline__ u32x4 pack8(f32x4 v0, f32x4 v1) { u32x4 w; w.x = cvt_pk_bf16(v0[0], v0[1]); w.y = cvt_pk_bf16(v0[2], v0[3]); w.z = cvt_pk_bf16(v1[0], v1[1]); w.w = cvt_pk_bf16(v1[2], v1[3]); return w; }
; #define GAS __attribute__((address_space(1)))
;     __device__ __forceinline__ void operator()(const f32x4 (&acc)[2][2][4][2], const Unit& u, int wr, int wc, int fr_in, int fq_in) const {
;     ...
;                         for (int n = 0; n < 2; ++n) y[bj][n] = y[bj][n] * rstd * gv[bj][n];
;                     f32x4 p0, p1;
; #pragma unroll
;                     for (int i = 0; i < 4; ++i) { p0[i] = __shfl_xor(y[0][0][i], 16); p1[i] = __shfl_xor(y[0][1][i], 16); }
;                     if (fq == 0) { y[0][0] = y[0][0] * c0 - p0 * s0; y[0][1] = y[0][1] * c1 - p1 * s1; }
;                     else if (fq == 1) { y[0][0] = y[0][0] * c0 + p0 * s0; y[0][1] = y[0][1] * c1 + p1 * s1; }
;                     if (!isk) { bf16_t* qp = QN + (size_t)row * 1024 + (4 * (u.pn - 4) + wc) * 64 + 8 * fq;
;                         *(GAS u32x4*)(qp) = pack8(y[0][0], y[0][1]); *(GAS u32x4*)(qp + 32) = pack8(y[1][0], y[1][1]); }
;                     else { const int co = wc * 64 + 8 * fq; bf16_t* kp = KN + (size_t)row * 256 + co;
;                         *(GAS u32x4*)(kp) = pack8(y[0][0], y[0][1]); *(GAS u32x4*)(kp + 32) = pack8(y[1][0], y[1][1]);
;                         if (smp || t >= 1920) { float* d = out + (smp ? o_sk + ((size_t)(l * 16 + bb) * 128 + 64 + t) * 256 : o_pk + ((size_t)(l * 4 + bb) * 128 + (t - 1920)) * 256) + co;
;                             *(f32x4*)(d) = y[0][0]; *(f32x4*)(d + 4) = y[0][1]; *(f32x4*)(d + 32) = y[1][0]; *(f32x4*)(d + 36) = y[1][1]; } }
.LBB0_578:
	s_or_b64 exec, exec, s[56:57]
	v_pk_mul_f32 v[8:9], v[8:9], v[42:43]
	v_pk_mul_f32 v[6:7], v[6:7], v[40:41]
	v_pk_mul_f32 v[4:5], v[4:5], v[42:43]
	v_pk_mul_f32 v[2:3], v[2:3], v[40:41]
	v_pk_mul_f32 v[8:9], v[130:131], v[8:9]
	v_pk_mul_f32 v[6:7], v[128:129], v[6:7]
	v_pk_mul_f32 v[4:5], v[126:127], v[4:5]
	v_pk_mul_f32 v[2:3], v[124:125], v[2:3]
	v_ashrrev_i32_e32 v39, 31, v38
	s_mov_b64 s[56:57], -1
	s_and_b64 vcc, exec, s[38:39]
	s_waitcnt vmcnt(3)
	v_cvt_pk_bf16_f32 v22, v14, v15
	v_cvt_pk_bf16_f32 v23, v16, v17
	s_waitcnt vmcnt(1)
	v_cvt_pk_bf16_f32 v24, v10, v11
	v_cvt_pk_bf16_f32 v25, v12, v13
	s_waitcnt lgkmcnt(6)
	v_cvt_pk_bf16_f32 v18, v6, v7
	s_waitcnt lgkmcnt(4)
	v_cvt_pk_bf16_f32 v19, v8, v9
	v_cvt_pk_bf16_f32 v20, v2, v3
	v_cvt_pk_bf16_f32 v21, v4, v5
	s_cbranch_vccnz .LBB0_580
	v_lshlrev_b64 v[26:27], 11, v[38:39]
	s_lshl_b32 s0, s95, 8
	v_lshl_add_u64 v[26:27], s[22:23], 0, v[26:27]
	s_add_i32 s78, s0, s93
	v_lshl_add_u64 v[26:27], s[78:79], 1, v[26:27]
	v_lshl_add_u64 v[26:27], v[194:195], 1, v[26:27]
	s_mov_b64 s[56:57], 0
	global_store_dwordx4 v[26:27], v[22:25], off sc1
	global_store_dwordx4 v[26:27], v[18:21], off offset:64 sc1
.LBB0_580:
	s_andn2_b64 vcc, exec, s[56:57]
	s_cbranch_vccnz .LBB0_588
	v_lshlrev_b64 v[26:27], 9, v[38:39]
	s_movk_i32 s0, 0x77f
	v_lshl_add_u64 v[26:27], s[82:83], 0, v[26:27]
	v_cmp_lt_u32_e32 vcc, s0, v49
	v_lshl_add_u64 v[26:27], v[156:157], 1, v[26:27]
	s_or_b64 s[0:1], s[42:43], vcc
	global_store_dwordx4 v[26:27], v[22:25], off sc1
	global_store_dwordx4 v[26:27], v[18:21], off offset:64 sc1
	s_and_saveexec_b64 s[38:39], s[0:1]
	s_cbranch_execz .LBB0_587
	s_and_saveexec_b64 s[0:1], s[40:41]
	s_xor_b64 s[40:41], exec, s[0:1]
	v_ashrrev_i32_e32 v18, 11, v38
	v_add_u32_e32 v18, s75, v18
	v_ashrrev_i32_e32 v19, 31, v18
	v_lshlrev_b32_e32 v20, 8, v48
	v_mov_b32_e32 v21, v98
	v_lshlrev_b64 v[18:19], 15, v[18:19]
	v_lshl_add_u64 v[18:19], v[20:21], 0, v[18:19]
	s_mov_b64 s[0:1], 0x1188000
	v_lshl_add_u64 v[18:19], v[18:19], 0, s[0:1]
	s_andn2_saveexec_b64 s[40:41], s[40:41]
	v_add_u32_e32 v18, 0xffffe0b0, v192
	v_lshrrev_b32_e32 v18, 6, v18
	v_add_u32_e32 v18, s31, v18
	v_mov_b32_e32 v19, v98
	v_lshlrev_b64 v[18:19], 15, v[18:19]
	v_lshl_or_b32 v20, v114, 8, v217
	v_mov_b32_e32 v21, v98
	v_lshl_add_u64 v[18:19], v[18:19], 0, v[20:21]
	s_or_b64 exec, exec, s[40:41]
	v_lshl_add_u64 v[18:19], v[18:19], 2, s[64:65]
	v_lshl_add_u64 v[18:19], v[156:157], 2, v[18:19]
	global_store_dwordx4 v[18:19], v[14:17], off sc1
	global_store_dwordx4 v[18:19], v[10:13], off offset:16 sc1
	global_store_dwordx4 v[18:19], v[6:9], off offset:128 sc1
	global_store_dwordx4 v[18:19], v[2:5], off offset:144 sc1
